# scan: 2 accumulator chains instead of 4 for dot/readout (4 v_add fewer per step), MFMA result fused into sa fma
# speedup vs baseline: 1.1016x; 1.0112x over previous
.LBB0_583:
	s_and_b32 s48, s16, 1
	v_lshl_add_u32 v21, s48, 9, v135
	ds_read_b128 v[24:27], v21
	ds_read_b128 v[28:31], v21 offset:16
	v_fmac_f32_e32 v18, s52, v22
	s_mul_i32 s52, s48, 0x6000
	v_fmac_f32_e32 v18, s17, v19
	s_add_i32 s17, s52, 0
	v_add3_u32 v19, s17, v157, v72
	v_lshl_add_u32 v21, v73, 2, s17
	ds_read2st64_b32 v[32:33], v19 offset0:80 offset1:81
	ds_read2st64_b32 v[34:35], v21 offset0:16 offset1:17
	ds_read2st64_b32 v[36:37], v21 offset0:32 offset1:33
	ds_read2st64_b32 v[38:39], v21 offset0:48 offset1:49
	ds_read2st64_b32 v[40:41], v21 offset0:64 offset1:65
	s_waitcnt lgkmcnt(6)
	v_mov_b32_e32 v42, v24
	s_waitcnt lgkmcnt(5)
	v_mov_b32_e32 v43, v28
	v_mov_b32_e32 v44, v26
	v_mov_b32_e32 v45, v30
	v_mov_b32_e32 v28, v25
	v_mov_b32_e32 v30, v27
	v_pk_add_f32 v[24:25], v[42:43], v[44:45]
	v_pk_add_f32 v[26:27], v[28:29], v[30:31]
	s_waitcnt lgkmcnt(3)
	v_mul_f32_dpp v42, v34, v17 row_newbcast:0 row_mask:0xf bank_mask:0xf bound_ctrl:1
	v_add_f32_e32 v23, v24, v25
	v_add_f32_e32 v24, v26, v27
	v_mul_f32_dpp v25, v34, v16 row_newbcast:1 row_mask:0xf bank_mask:0xf bound_ctrl:1
	v_fmac_f32_dpp v42, v34, v15 row_newbcast:2 row_mask:0xf bank_mask:0xf bound_ctrl:1
	v_fmac_f32_dpp v25, v34, v14 row_newbcast:3 row_mask:0xf bank_mask:0xf bound_ctrl:1
	v_fmac_f32_dpp v42, v34, v13 row_newbcast:4 row_mask:0xf bank_mask:0xf bound_ctrl:1
	v_xor_b32_e32 v23, 0x80000000, v23
	v_fmac_f32_dpp v25, v34, v12 row_newbcast:5 row_mask:0xf bank_mask:0xf bound_ctrl:1
	v_fmac_f32_dpp v42, v34, v11 row_newbcast:6 row_mask:0xf bank_mask:0xf bound_ctrl:1
	v_fmac_f32_dpp v25, v34, v10 row_newbcast:7 row_mask:0xf bank_mask:0xf bound_ctrl:1
	v_fmac_f32_dpp v42, v34, v9 row_newbcast:8 row_mask:0xf bank_mask:0xf bound_ctrl:1
	v_xor_b32_e32 v24, 0x80000000, v24
	v_fmac_f32_dpp v25, v34, v8 row_newbcast:9 row_mask:0xf bank_mask:0xf bound_ctrl:1
	v_fmac_f32_dpp v42, v34, v7 row_newbcast:10 row_mask:0xf bank_mask:0xf bound_ctrl:1
	v_fmac_f32_dpp v25, v34, v6 row_newbcast:11 row_mask:0xf bank_mask:0xf bound_ctrl:1
	v_fmac_f32_dpp v42, v34, v5 row_newbcast:12 row_mask:0xf bank_mask:0xf bound_ctrl:1
	v_readlane_b32 s97, v23, 0
	v_fmac_f32_dpp v25, v34, v4 row_newbcast:13 row_mask:0xf bank_mask:0xf bound_ctrl:1
	v_fmac_f32_dpp v42, v34, v3 row_newbcast:14 row_mask:0xf bank_mask:0xf bound_ctrl:1
	v_fmac_f32_dpp v25, v34, v2 row_newbcast:15 row_mask:0xf bank_mask:0xf bound_ctrl:1
	s_waitcnt lgkmcnt(2)
	v_fmac_f32_dpp v17, v36, v18 row_newbcast:0 row_mask:0xf bank_mask:0xf bound_ctrl:1
	v_fmac_f32_dpp v16, v36, v18 row_newbcast:1 row_mask:0xf bank_mask:0xf bound_ctrl:1
	v_fmac_f32_dpp v15, v36, v18 row_newbcast:2 row_mask:0xf bank_mask:0xf bound_ctrl:1
	v_fmac_f32_dpp v14, v36, v18 row_newbcast:3 row_mask:0xf bank_mask:0xf bound_ctrl:1
	v_fmac_f32_dpp v13, v36, v18 row_newbcast:4 row_mask:0xf bank_mask:0xf bound_ctrl:1
	v_fmac_f32_dpp v12, v36, v18 row_newbcast:5 row_mask:0xf bank_mask:0xf bound_ctrl:1
	v_fmac_f32_dpp v11, v36, v18 row_newbcast:6 row_mask:0xf bank_mask:0xf bound_ctrl:1
	v_fmac_f32_dpp v10, v36, v18 row_newbcast:7 row_mask:0xf bank_mask:0xf bound_ctrl:1
	v_fmac_f32_dpp v9, v36, v18 row_newbcast:8 row_mask:0xf bank_mask:0xf bound_ctrl:1
	v_fmac_f32_dpp v8, v36, v18 row_newbcast:9 row_mask:0xf bank_mask:0xf bound_ctrl:1
	v_fmac_f32_dpp v7, v36, v18 row_newbcast:10 row_mask:0xf bank_mask:0xf bound_ctrl:1
	v_fmac_f32_dpp v6, v36, v18 row_newbcast:11 row_mask:0xf bank_mask:0xf bound_ctrl:1
	v_fmac_f32_dpp v5, v36, v18 row_newbcast:12 row_mask:0xf bank_mask:0xf bound_ctrl:1
	v_fmac_f32_dpp v4, v36, v18 row_newbcast:13 row_mask:0xf bank_mask:0xf bound_ctrl:1
	v_fmac_f32_dpp v3, v36, v18 row_newbcast:14 row_mask:0xf bank_mask:0xf bound_ctrl:1
	v_fmac_f32_dpp v2, v36, v18 row_newbcast:15 row_mask:0xf bank_mask:0xf bound_ctrl:1
	v_add_f32 v42, v42, v25
	v_readlane_b32 vcc_hi, v23, 1
	v_readlane_b32 s96, v23, 2
	v_readlane_b32 s94, v23, 3
	v_readlane_b32 s92, v23, 4
	v_readlane_b32 s90, v23, 5
	v_readlane_b32 s88, v23, 6
	v_readlane_b32 s82, v23, 7
	v_readlane_b32 s80, v23, 8
	v_readlane_b32 s67, v23, 9
	v_readlane_b32 s65, v23, 10
	v_readlane_b32 s63, v23, 11
	v_readlane_b32 s59, v23, 12
	v_readlane_b32 s57, v23, 13
	v_readlane_b32 s53, v23, 14
	v_readlane_b32 s52, v23, 15
	v_lshl_add_u32 v22, s48, 15, v134
	s_nop 1
	v_mfma_f32_16x16x4_f32 v[224:227], v228, v42, 0
	v_readlane_b32 vcc_lo, v24, 0
	v_readlane_b32 s28, v24, 1
	v_readlane_b32 s95, v24, 2
	v_readlane_b32 s93, v24, 3
	v_readlane_b32 s91, v24, 4
	v_readlane_b32 s89, v24, 5
	v_readlane_b32 s83, v24, 6
	v_readlane_b32 s81, v24, 7
	v_readlane_b32 s79, v24, 8
	v_readlane_b32 s66, v24, 9
	v_readlane_b32 s64, v24, 10
	v_readlane_b32 s62, v24, 11
	v_readlane_b32 s58, v24, 12
	v_readlane_b32 s56, v24, 13
	v_readlane_b32 s48, v24, 14
	v_readlane_b32 s17, v24, 15
	s_waitcnt lgkmcnt(1)
	v_fmac_f32_dpp v17, v38, v32 row_newbcast:0 row_mask:0xf bank_mask:0xf bound_ctrl:1
	v_fmac_f32_dpp v16, v38, v32 row_newbcast:1 row_mask:0xf bank_mask:0xf bound_ctrl:1
	v_fmac_f32_dpp v15, v38, v32 row_newbcast:2 row_mask:0xf bank_mask:0xf bound_ctrl:1
	v_fmac_f32_dpp v14, v38, v32 row_newbcast:3 row_mask:0xf bank_mask:0xf bound_ctrl:1
	v_fmac_f32_dpp v13, v38, v32 row_newbcast:4 row_mask:0xf bank_mask:0xf bound_ctrl:1
	v_fmac_f32_dpp v12, v38, v32 row_newbcast:5 row_mask:0xf bank_mask:0xf bound_ctrl:1
	v_fmac_f32_dpp v11, v38, v32 row_newbcast:6 row_mask:0xf bank_mask:0xf bound_ctrl:1
	v_fmac_f32_dpp v10, v38, v32 row_newbcast:7 row_mask:0xf bank_mask:0xf bound_ctrl:1
	v_fmac_f32_dpp v9, v38, v32 row_newbcast:8 row_mask:0xf bank_mask:0xf bound_ctrl:1
	v_fmac_f32_dpp v8, v38, v32 row_newbcast:9 row_mask:0xf bank_mask:0xf bound_ctrl:1
	v_fmac_f32_dpp v7, v38, v32 row_newbcast:10 row_mask:0xf bank_mask:0xf bound_ctrl:1
	v_fmac_f32_dpp v6, v38, v32 row_newbcast:11 row_mask:0xf bank_mask:0xf bound_ctrl:1
	v_fmac_f32_dpp v5, v38, v32 row_newbcast:12 row_mask:0xf bank_mask:0xf bound_ctrl:1
	v_fmac_f32_dpp v4, v38, v32 row_newbcast:13 row_mask:0xf bank_mask:0xf bound_ctrl:1
	v_fmac_f32_dpp v3, v38, v32 row_newbcast:14 row_mask:0xf bank_mask:0xf bound_ctrl:1
	v_fmac_f32_dpp v2, v38, v32 row_newbcast:15 row_mask:0xf bank_mask:0xf bound_ctrl:1
	s_waitcnt lgkmcnt(0)
	v_mul_f32_dpp v24, v40, v17 row_newbcast:0 row_mask:0xf bank_mask:0xf bound_ctrl:1
	v_mul_f32_dpp v25, v40, v16 row_newbcast:1 row_mask:0xf bank_mask:0xf bound_ctrl:1
	v_fmac_f32_dpp v24, v40, v15 row_newbcast:2 row_mask:0xf bank_mask:0xf bound_ctrl:1
	v_fmac_f32_dpp v25, v40, v14 row_newbcast:3 row_mask:0xf bank_mask:0xf bound_ctrl:1
	v_fmac_f32_dpp v24, v40, v13 row_newbcast:4 row_mask:0xf bank_mask:0xf bound_ctrl:1
	v_fmac_f32_dpp v25, v40, v12 row_newbcast:5 row_mask:0xf bank_mask:0xf bound_ctrl:1
	v_fmac_f32_dpp v24, v40, v11 row_newbcast:6 row_mask:0xf bank_mask:0xf bound_ctrl:1
	v_fmac_f32_dpp v25, v40, v10 row_newbcast:7 row_mask:0xf bank_mask:0xf bound_ctrl:1
	v_add_u32_e32 v20, 0xc000, v22
	v_fmac_f32_dpp v24, v40, v9 row_newbcast:8 row_mask:0xf bank_mask:0xf bound_ctrl:1
	v_fmac_f32_dpp v25, v40, v8 row_newbcast:9 row_mask:0xf bank_mask:0xf bound_ctrl:1
	v_fmac_f32_dpp v24, v40, v7 row_newbcast:10 row_mask:0xf bank_mask:0xf bound_ctrl:1
	v_fmac_f32_dpp v25, v40, v6 row_newbcast:11 row_mask:0xf bank_mask:0xf bound_ctrl:1
	s_add_i32 s16, s16, 1
	v_fmac_f32_dpp v24, v40, v5 row_newbcast:12 row_mask:0xf bank_mask:0xf bound_ctrl:1
	v_fmac_f32_dpp v25, v40, v4 row_newbcast:13 row_mask:0xf bank_mask:0xf bound_ctrl:1
	v_fmac_f32_dpp v24, v40, v3 row_newbcast:14 row_mask:0xf bank_mask:0xf bound_ctrl:1
	v_fmac_f32_dpp v25, v40, v2 row_newbcast:15 row_mask:0xf bank_mask:0xf bound_ctrl:1
	ds_read_b32 v36, v19 offset:20992
	ds_read2st64_b32 v[26:27], v21 offset0:18 offset1:34
	ds_read2st64_b32 v[28:29], v21 offset0:50 offset1:66
	v_mul_f32_dpp v38, v35, v17 row_newbcast:0 row_mask:0xf bank_mask:0xf bound_ctrl:1
	v_mul_f32_dpp v31, v35, v16 row_newbcast:1 row_mask:0xf bank_mask:0xf bound_ctrl:1
	v_fmac_f32_dpp v38, v35, v15 row_newbcast:2 row_mask:0xf bank_mask:0xf bound_ctrl:1
	v_fmac_f32_dpp v31, v35, v14 row_newbcast:3 row_mask:0xf bank_mask:0xf bound_ctrl:1
	v_fma_f32 v42, s97, v18, v224
	v_fmac_f32_dpp v38, v35, v13 row_newbcast:4 row_mask:0xf bank_mask:0xf bound_ctrl:1
	v_fmac_f32_dpp v31, v35, v12 row_newbcast:5 row_mask:0xf bank_mask:0xf bound_ctrl:1
	v_fmac_f32_dpp v38, v35, v11 row_newbcast:6 row_mask:0xf bank_mask:0xf bound_ctrl:1
	v_fmac_f32_dpp v31, v35, v10 row_newbcast:7 row_mask:0xf bank_mask:0xf bound_ctrl:1
	v_fmac_f32_e32 v42, vcc_lo, v32
	v_fmac_f32_dpp v38, v35, v9 row_newbcast:8 row_mask:0xf bank_mask:0xf bound_ctrl:1
	v_fmac_f32_dpp v31, v35, v8 row_newbcast:9 row_mask:0xf bank_mask:0xf bound_ctrl:1
	v_fmac_f32_dpp v38, v35, v7 row_newbcast:10 row_mask:0xf bank_mask:0xf bound_ctrl:1
	v_fmac_f32_dpp v31, v35, v6 row_newbcast:11 row_mask:0xf bank_mask:0xf bound_ctrl:1
	s_cmpk_lg_i32 s16, 0x210
	v_fmac_f32_dpp v38, v35, v5 row_newbcast:12 row_mask:0xf bank_mask:0xf bound_ctrl:1
	v_fmac_f32_dpp v31, v35, v4 row_newbcast:13 row_mask:0xf bank_mask:0xf bound_ctrl:1
	v_fmac_f32_dpp v38, v35, v3 row_newbcast:14 row_mask:0xf bank_mask:0xf bound_ctrl:1
	v_fmac_f32_dpp v31, v35, v2 row_newbcast:15 row_mask:0xf bank_mask:0xf bound_ctrl:1
	v_fmac_f32_dpp v17, v37, v42 row_newbcast:0 row_mask:0xf bank_mask:0xf bound_ctrl:1
	v_fmac_f32_dpp v16, v37, v42 row_newbcast:1 row_mask:0xf bank_mask:0xf bound_ctrl:1
	v_fmac_f32_dpp v15, v37, v42 row_newbcast:2 row_mask:0xf bank_mask:0xf bound_ctrl:1
	v_fmac_f32_dpp v14, v37, v42 row_newbcast:3 row_mask:0xf bank_mask:0xf bound_ctrl:1
	v_fmac_f32_dpp v13, v37, v42 row_newbcast:4 row_mask:0xf bank_mask:0xf bound_ctrl:1
	v_fmac_f32_dpp v12, v37, v42 row_newbcast:5 row_mask:0xf bank_mask:0xf bound_ctrl:1
	v_fmac_f32_dpp v11, v37, v42 row_newbcast:6 row_mask:0xf bank_mask:0xf bound_ctrl:1
	v_fmac_f32_dpp v10, v37, v42 row_newbcast:7 row_mask:0xf bank_mask:0xf bound_ctrl:1
	v_fmac_f32_dpp v9, v37, v42 row_newbcast:8 row_mask:0xf bank_mask:0xf bound_ctrl:1
	v_fmac_f32_dpp v8, v37, v42 row_newbcast:9 row_mask:0xf bank_mask:0xf bound_ctrl:1
	v_fmac_f32_dpp v7, v37, v42 row_newbcast:10 row_mask:0xf bank_mask:0xf bound_ctrl:1
	v_fmac_f32_dpp v6, v37, v42 row_newbcast:11 row_mask:0xf bank_mask:0xf bound_ctrl:1
	v_fmac_f32_dpp v5, v37, v42 row_newbcast:12 row_mask:0xf bank_mask:0xf bound_ctrl:1
	v_fmac_f32_dpp v4, v37, v42 row_newbcast:13 row_mask:0xf bank_mask:0xf bound_ctrl:1
	v_fmac_f32_dpp v3, v37, v42 row_newbcast:14 row_mask:0xf bank_mask:0xf bound_ctrl:1
	v_fmac_f32_dpp v2, v37, v42 row_newbcast:15 row_mask:0xf bank_mask:0xf bound_ctrl:1
	s_nop 0
	v_add_f32 v38, v38, v31
	s_nop 0
	s_nop 0
	v_mfma_f32_16x16x4_f32 v[224:227], v228, v38, 0
	ds_write_b64 v22, v[24:25] offset:49152
	v_fmac_f32_dpp v17, v39, v33 row_newbcast:0 row_mask:0xf bank_mask:0xf bound_ctrl:1
	v_fmac_f32_dpp v16, v39, v33 row_newbcast:1 row_mask:0xf bank_mask:0xf bound_ctrl:1
	v_fmac_f32_dpp v15, v39, v33 row_newbcast:2 row_mask:0xf bank_mask:0xf bound_ctrl:1
	v_fmac_f32_dpp v14, v39, v33 row_newbcast:3 row_mask:0xf bank_mask:0xf bound_ctrl:1
	v_fmac_f32_dpp v13, v39, v33 row_newbcast:4 row_mask:0xf bank_mask:0xf bound_ctrl:1
	v_fmac_f32_dpp v12, v39, v33 row_newbcast:5 row_mask:0xf bank_mask:0xf bound_ctrl:1
	v_fmac_f32_dpp v11, v39, v33 row_newbcast:6 row_mask:0xf bank_mask:0xf bound_ctrl:1
	v_fmac_f32_dpp v10, v39, v33 row_newbcast:7 row_mask:0xf bank_mask:0xf bound_ctrl:1
	v_fmac_f32_dpp v9, v39, v33 row_newbcast:8 row_mask:0xf bank_mask:0xf bound_ctrl:1
	v_fmac_f32_dpp v8, v39, v33 row_newbcast:9 row_mask:0xf bank_mask:0xf bound_ctrl:1
	v_fmac_f32_dpp v7, v39, v33 row_newbcast:10 row_mask:0xf bank_mask:0xf bound_ctrl:1
	v_fmac_f32_dpp v6, v39, v33 row_newbcast:11 row_mask:0xf bank_mask:0xf bound_ctrl:1
	v_fmac_f32_dpp v5, v39, v33 row_newbcast:12 row_mask:0xf bank_mask:0xf bound_ctrl:1
	v_fmac_f32_dpp v4, v39, v33 row_newbcast:13 row_mask:0xf bank_mask:0xf bound_ctrl:1
	v_fmac_f32_dpp v3, v39, v33 row_newbcast:14 row_mask:0xf bank_mask:0xf bound_ctrl:1
	v_fmac_f32_dpp v2, v39, v33 row_newbcast:15 row_mask:0xf bank_mask:0xf bound_ctrl:1
	v_mul_f32_dpp v24, v41, v17 row_newbcast:0 row_mask:0xf bank_mask:0xf bound_ctrl:1
	v_mul_f32_dpp v25, v41, v16 row_newbcast:1 row_mask:0xf bank_mask:0xf bound_ctrl:1
	v_fmac_f32_dpp v24, v41, v15 row_newbcast:2 row_mask:0xf bank_mask:0xf bound_ctrl:1
	v_fmac_f32_dpp v25, v41, v14 row_newbcast:3 row_mask:0xf bank_mask:0xf bound_ctrl:1
	v_fmac_f32_dpp v24, v41, v13 row_newbcast:4 row_mask:0xf bank_mask:0xf bound_ctrl:1
	v_fmac_f32_dpp v25, v41, v12 row_newbcast:5 row_mask:0xf bank_mask:0xf bound_ctrl:1
	v_fmac_f32_dpp v24, v41, v11 row_newbcast:6 row_mask:0xf bank_mask:0xf bound_ctrl:1
	v_fmac_f32_dpp v25, v41, v10 row_newbcast:7 row_mask:0xf bank_mask:0xf bound_ctrl:1
	s_nop 0
	v_fmac_f32_dpp v24, v41, v9 row_newbcast:8 row_mask:0xf bank_mask:0xf bound_ctrl:1
	v_fmac_f32_dpp v25, v41, v8 row_newbcast:9 row_mask:0xf bank_mask:0xf bound_ctrl:1
	v_fmac_f32_dpp v24, v41, v7 row_newbcast:10 row_mask:0xf bank_mask:0xf bound_ctrl:1
	v_fmac_f32_dpp v25, v41, v6 row_newbcast:11 row_mask:0xf bank_mask:0xf bound_ctrl:1
	s_nop 0
	v_fmac_f32_dpp v24, v41, v5 row_newbcast:12 row_mask:0xf bank_mask:0xf bound_ctrl:1
	v_fmac_f32_dpp v25, v41, v4 row_newbcast:13 row_mask:0xf bank_mask:0xf bound_ctrl:1
	v_fmac_f32_dpp v24, v41, v3 row_newbcast:14 row_mask:0xf bank_mask:0xf bound_ctrl:1
	v_fmac_f32_dpp v25, v41, v2 row_newbcast:15 row_mask:0xf bank_mask:0xf bound_ctrl:1
	s_waitcnt lgkmcnt(0)
	ds_read_b32 v37, v19 offset:21248
	ds_read2st64_b32 v[30:31], v21 offset0:19 offset1:35
	ds_read2st64_b32 v[34:35], v21 offset0:51 offset1:67
	v_mul_f32_dpp v39, v26, v17 row_newbcast:0 row_mask:0xf bank_mask:0xf bound_ctrl:1
	v_mul_f32_dpp v32, v26, v16 row_newbcast:1 row_mask:0xf bank_mask:0xf bound_ctrl:1
	v_fmac_f32_dpp v39, v26, v15 row_newbcast:2 row_mask:0xf bank_mask:0xf bound_ctrl:1
	v_fmac_f32_dpp v32, v26, v14 row_newbcast:3 row_mask:0xf bank_mask:0xf bound_ctrl:1
	v_fma_f32 v38, vcc_hi, v42, v224
	v_fmac_f32_dpp v39, v26, v13 row_newbcast:4 row_mask:0xf bank_mask:0xf bound_ctrl:1
	v_fmac_f32_dpp v32, v26, v12 row_newbcast:5 row_mask:0xf bank_mask:0xf bound_ctrl:1
	v_fmac_f32_dpp v39, v26, v11 row_newbcast:6 row_mask:0xf bank_mask:0xf bound_ctrl:1
	v_fmac_f32_dpp v32, v26, v10 row_newbcast:7 row_mask:0xf bank_mask:0xf bound_ctrl:1
	v_fmac_f32_e32 v38, s28, v33
	v_fmac_f32_dpp v39, v26, v9 row_newbcast:8 row_mask:0xf bank_mask:0xf bound_ctrl:1
	v_fmac_f32_dpp v32, v26, v8 row_newbcast:9 row_mask:0xf bank_mask:0xf bound_ctrl:1
	v_fmac_f32_dpp v39, v26, v7 row_newbcast:10 row_mask:0xf bank_mask:0xf bound_ctrl:1
	v_fmac_f32_dpp v32, v26, v6 row_newbcast:11 row_mask:0xf bank_mask:0xf bound_ctrl:1
	s_nop 0
	v_fmac_f32_dpp v39, v26, v5 row_newbcast:12 row_mask:0xf bank_mask:0xf bound_ctrl:1
	v_fmac_f32_dpp v32, v26, v4 row_newbcast:13 row_mask:0xf bank_mask:0xf bound_ctrl:1
	v_fmac_f32_dpp v39, v26, v3 row_newbcast:14 row_mask:0xf bank_mask:0xf bound_ctrl:1
	v_fmac_f32_dpp v32, v26, v2 row_newbcast:15 row_mask:0xf bank_mask:0xf bound_ctrl:1
	v_fmac_f32_dpp v17, v27, v38 row_newbcast:0 row_mask:0xf bank_mask:0xf bound_ctrl:1
	v_fmac_f32_dpp v16, v27, v38 row_newbcast:1 row_mask:0xf bank_mask:0xf bound_ctrl:1
	v_fmac_f32_dpp v15, v27, v38 row_newbcast:2 row_mask:0xf bank_mask:0xf bound_ctrl:1
	v_fmac_f32_dpp v14, v27, v38 row_newbcast:3 row_mask:0xf bank_mask:0xf bound_ctrl:1
	v_fmac_f32_dpp v13, v27, v38 row_newbcast:4 row_mask:0xf bank_mask:0xf bound_ctrl:1
	v_fmac_f32_dpp v12, v27, v38 row_newbcast:5 row_mask:0xf bank_mask:0xf bound_ctrl:1
	v_fmac_f32_dpp v11, v27, v38 row_newbcast:6 row_mask:0xf bank_mask:0xf bound_ctrl:1
	v_fmac_f32_dpp v10, v27, v38 row_newbcast:7 row_mask:0xf bank_mask:0xf bound_ctrl:1
	v_fmac_f32_dpp v9, v27, v38 row_newbcast:8 row_mask:0xf bank_mask:0xf bound_ctrl:1
	v_fmac_f32_dpp v8, v27, v38 row_newbcast:9 row_mask:0xf bank_mask:0xf bound_ctrl:1
	v_fmac_f32_dpp v7, v27, v38 row_newbcast:10 row_mask:0xf bank_mask:0xf bound_ctrl:1
	v_fmac_f32_dpp v6, v27, v38 row_newbcast:11 row_mask:0xf bank_mask:0xf bound_ctrl:1
	v_fmac_f32_dpp v5, v27, v38 row_newbcast:12 row_mask:0xf bank_mask:0xf bound_ctrl:1
	v_fmac_f32_dpp v4, v27, v38 row_newbcast:13 row_mask:0xf bank_mask:0xf bound_ctrl:1
	v_fmac_f32_dpp v3, v27, v38 row_newbcast:14 row_mask:0xf bank_mask:0xf bound_ctrl:1
	v_fmac_f32_dpp v2, v27, v38 row_newbcast:15 row_mask:0xf bank_mask:0xf bound_ctrl:1
	s_nop 0
	v_add_f32 v39, v39, v32
	s_nop 0
	s_nop 0
	v_mfma_f32_16x16x4_f32 v[224:227], v228, v39, 0
	ds_write_b64 v22, v[24:25] offset:51200
	v_fmac_f32_dpp v17, v28, v36 row_newbcast:0 row_mask:0xf bank_mask:0xf bound_ctrl:1
	v_fmac_f32_dpp v16, v28, v36 row_newbcast:1 row_mask:0xf bank_mask:0xf bound_ctrl:1
	v_fmac_f32_dpp v15, v28, v36 row_newbcast:2 row_mask:0xf bank_mask:0xf bound_ctrl:1
	v_fmac_f32_dpp v14, v28, v36 row_newbcast:3 row_mask:0xf bank_mask:0xf bound_ctrl:1
	v_fmac_f32_dpp v13, v28, v36 row_newbcast:4 row_mask:0xf bank_mask:0xf bound_ctrl:1
	v_fmac_f32_dpp v12, v28, v36 row_newbcast:5 row_mask:0xf bank_mask:0xf bound_ctrl:1
	v_fmac_f32_dpp v11, v28, v36 row_newbcast:6 row_mask:0xf bank_mask:0xf bound_ctrl:1
	v_fmac_f32_dpp v10, v28, v36 row_newbcast:7 row_mask:0xf bank_mask:0xf bound_ctrl:1
	v_fmac_f32_dpp v9, v28, v36 row_newbcast:8 row_mask:0xf bank_mask:0xf bound_ctrl:1
	v_fmac_f32_dpp v8, v28, v36 row_newbcast:9 row_mask:0xf bank_mask:0xf bound_ctrl:1
	v_fmac_f32_dpp v7, v28, v36 row_newbcast:10 row_mask:0xf bank_mask:0xf bound_ctrl:1
	v_fmac_f32_dpp v6, v28, v36 row_newbcast:11 row_mask:0xf bank_mask:0xf bound_ctrl:1
	v_fmac_f32_dpp v5, v28, v36 row_newbcast:12 row_mask:0xf bank_mask:0xf bound_ctrl:1
	v_fmac_f32_dpp v4, v28, v36 row_newbcast:13 row_mask:0xf bank_mask:0xf bound_ctrl:1
	v_fmac_f32_dpp v3, v28, v36 row_newbcast:14 row_mask:0xf bank_mask:0xf bound_ctrl:1
	v_fmac_f32_dpp v2, v28, v36 row_newbcast:15 row_mask:0xf bank_mask:0xf bound_ctrl:1
	v_mul_f32_dpp v24, v29, v17 row_newbcast:0 row_mask:0xf bank_mask:0xf bound_ctrl:1
	v_mul_f32_dpp v25, v29, v16 row_newbcast:1 row_mask:0xf bank_mask:0xf bound_ctrl:1
	v_fmac_f32_dpp v24, v29, v15 row_newbcast:2 row_mask:0xf bank_mask:0xf bound_ctrl:1
	v_fmac_f32_dpp v25, v29, v14 row_newbcast:3 row_mask:0xf bank_mask:0xf bound_ctrl:1
	v_fmac_f32_dpp v24, v29, v13 row_newbcast:4 row_mask:0xf bank_mask:0xf bound_ctrl:1
	v_fmac_f32_dpp v25, v29, v12 row_newbcast:5 row_mask:0xf bank_mask:0xf bound_ctrl:1
	v_fmac_f32_dpp v24, v29, v11 row_newbcast:6 row_mask:0xf bank_mask:0xf bound_ctrl:1
	v_fmac_f32_dpp v25, v29, v10 row_newbcast:7 row_mask:0xf bank_mask:0xf bound_ctrl:1
	s_nop 0
	v_fmac_f32_dpp v24, v29, v9 row_newbcast:8 row_mask:0xf bank_mask:0xf bound_ctrl:1
	v_fmac_f32_dpp v25, v29, v8 row_newbcast:9 row_mask:0xf bank_mask:0xf bound_ctrl:1
	v_fmac_f32_dpp v24, v29, v7 row_newbcast:10 row_mask:0xf bank_mask:0xf bound_ctrl:1
	v_fmac_f32_dpp v25, v29, v6 row_newbcast:11 row_mask:0xf bank_mask:0xf bound_ctrl:1
	s_nop 0
	v_fmac_f32_dpp v24, v29, v5 row_newbcast:12 row_mask:0xf bank_mask:0xf bound_ctrl:1
	v_fmac_f32_dpp v25, v29, v4 row_newbcast:13 row_mask:0xf bank_mask:0xf bound_ctrl:1
	v_fmac_f32_dpp v24, v29, v3 row_newbcast:14 row_mask:0xf bank_mask:0xf bound_ctrl:1
	v_fmac_f32_dpp v25, v29, v2 row_newbcast:15 row_mask:0xf bank_mask:0xf bound_ctrl:1
	s_waitcnt lgkmcnt(0)
	ds_read_b32 v40, v19 offset:21504
	ds_read2st64_b32 v[26:27], v21 offset0:20 offset1:36
	ds_read2st64_b32 v[28:29], v21 offset0:52 offset1:68
	v_mul_f32_dpp v41, v30, v17 row_newbcast:0 row_mask:0xf bank_mask:0xf bound_ctrl:1
	v_mul_f32_dpp v32, v30, v16 row_newbcast:1 row_mask:0xf bank_mask:0xf bound_ctrl:1
	v_fmac_f32_dpp v41, v30, v15 row_newbcast:2 row_mask:0xf bank_mask:0xf bound_ctrl:1
	v_fmac_f32_dpp v32, v30, v14 row_newbcast:3 row_mask:0xf bank_mask:0xf bound_ctrl:1
	v_fma_f32 v39, s96, v38, v224
	v_fmac_f32_dpp v41, v30, v13 row_newbcast:4 row_mask:0xf bank_mask:0xf bound_ctrl:1
	v_fmac_f32_dpp v32, v30, v12 row_newbcast:5 row_mask:0xf bank_mask:0xf bound_ctrl:1
	v_fmac_f32_dpp v41, v30, v11 row_newbcast:6 row_mask:0xf bank_mask:0xf bound_ctrl:1
	v_fmac_f32_dpp v32, v30, v10 row_newbcast:7 row_mask:0xf bank_mask:0xf bound_ctrl:1
	v_fmac_f32_e32 v39, s95, v36
	v_fmac_f32_dpp v41, v30, v9 row_newbcast:8 row_mask:0xf bank_mask:0xf bound_ctrl:1
	v_fmac_f32_dpp v32, v30, v8 row_newbcast:9 row_mask:0xf bank_mask:0xf bound_ctrl:1
	v_fmac_f32_dpp v41, v30, v7 row_newbcast:10 row_mask:0xf bank_mask:0xf bound_ctrl:1
	v_fmac_f32_dpp v32, v30, v6 row_newbcast:11 row_mask:0xf bank_mask:0xf bound_ctrl:1
	s_nop 0
	v_fmac_f32_dpp v41, v30, v5 row_newbcast:12 row_mask:0xf bank_mask:0xf bound_ctrl:1
	v_fmac_f32_dpp v32, v30, v4 row_newbcast:13 row_mask:0xf bank_mask:0xf bound_ctrl:1
	v_fmac_f32_dpp v41, v30, v3 row_newbcast:14 row_mask:0xf bank_mask:0xf bound_ctrl:1
	v_fmac_f32_dpp v32, v30, v2 row_newbcast:15 row_mask:0xf bank_mask:0xf bound_ctrl:1
	v_fmac_f32_dpp v17, v31, v39 row_newbcast:0 row_mask:0xf bank_mask:0xf bound_ctrl:1
	v_fmac_f32_dpp v16, v31, v39 row_newbcast:1 row_mask:0xf bank_mask:0xf bound_ctrl:1
	v_fmac_f32_dpp v15, v31, v39 row_newbcast:2 row_mask:0xf bank_mask:0xf bound_ctrl:1
	v_fmac_f32_dpp v14, v31, v39 row_newbcast:3 row_mask:0xf bank_mask:0xf bound_ctrl:1
	v_fmac_f32_dpp v13, v31, v39 row_newbcast:4 row_mask:0xf bank_mask:0xf bound_ctrl:1
	v_fmac_f32_dpp v12, v31, v39 row_newbcast:5 row_mask:0xf bank_mask:0xf bound_ctrl:1
	v_fmac_f32_dpp v11, v31, v39 row_newbcast:6 row_mask:0xf bank_mask:0xf bound_ctrl:1
	v_fmac_f32_dpp v10, v31, v39 row_newbcast:7 row_mask:0xf bank_mask:0xf bound_ctrl:1
	v_fmac_f32_dpp v9, v31, v39 row_newbcast:8 row_mask:0xf bank_mask:0xf bound_ctrl:1
	v_fmac_f32_dpp v8, v31, v39 row_newbcast:9 row_mask:0xf bank_mask:0xf bound_ctrl:1
	v_fmac_f32_dpp v7, v31, v39 row_newbcast:10 row_mask:0xf bank_mask:0xf bound_ctrl:1
	v_fmac_f32_dpp v6, v31, v39 row_newbcast:11 row_mask:0xf bank_mask:0xf bound_ctrl:1
	v_fmac_f32_dpp v5, v31, v39 row_newbcast:12 row_mask:0xf bank_mask:0xf bound_ctrl:1
	v_fmac_f32_dpp v4, v31, v39 row_newbcast:13 row_mask:0xf bank_mask:0xf bound_ctrl:1
	v_fmac_f32_dpp v3, v31, v39 row_newbcast:14 row_mask:0xf bank_mask:0xf bound_ctrl:1
	v_fmac_f32_dpp v2, v31, v39 row_newbcast:15 row_mask:0xf bank_mask:0xf bound_ctrl:1
	s_nop 0
	v_add_f32 v41, v41, v32
	s_nop 0
	s_nop 0
	v_mfma_f32_16x16x4_f32 v[224:227], v228, v41, 0
	ds_write_b64 v22, v[24:25] offset:53248
	v_fmac_f32_dpp v17, v34, v37 row_newbcast:0 row_mask:0xf bank_mask:0xf bound_ctrl:1
	v_fmac_f32_dpp v16, v34, v37 row_newbcast:1 row_mask:0xf bank_mask:0xf bound_ctrl:1
	v_fmac_f32_dpp v15, v34, v37 row_newbcast:2 row_mask:0xf bank_mask:0xf bound_ctrl:1
	v_fmac_f32_dpp v14, v34, v37 row_newbcast:3 row_mask:0xf bank_mask:0xf bound_ctrl:1
	v_fmac_f32_dpp v13, v34, v37 row_newbcast:4 row_mask:0xf bank_mask:0xf bound_ctrl:1
	v_fmac_f32_dpp v12, v34, v37 row_newbcast:5 row_mask:0xf bank_mask:0xf bound_ctrl:1
	v_fmac_f32_dpp v11, v34, v37 row_newbcast:6 row_mask:0xf bank_mask:0xf bound_ctrl:1
	v_fmac_f32_dpp v10, v34, v37 row_newbcast:7 row_mask:0xf bank_mask:0xf bound_ctrl:1
	v_fmac_f32_dpp v9, v34, v37 row_newbcast:8 row_mask:0xf bank_mask:0xf bound_ctrl:1
	v_fmac_f32_dpp v8, v34, v37 row_newbcast:9 row_mask:0xf bank_mask:0xf bound_ctrl:1
	v_fmac_f32_dpp v7, v34, v37 row_newbcast:10 row_mask:0xf bank_mask:0xf bound_ctrl:1
	v_fmac_f32_dpp v6, v34, v37 row_newbcast:11 row_mask:0xf bank_mask:0xf bound_ctrl:1
	v_fmac_f32_dpp v5, v34, v37 row_newbcast:12 row_mask:0xf bank_mask:0xf bound_ctrl:1
	v_fmac_f32_dpp v4, v34, v37 row_newbcast:13 row_mask:0xf bank_mask:0xf bound_ctrl:1
	v_fmac_f32_dpp v3, v34, v37 row_newbcast:14 row_mask:0xf bank_mask:0xf bound_ctrl:1
	v_fmac_f32_dpp v2, v34, v37 row_newbcast:15 row_mask:0xf bank_mask:0xf bound_ctrl:1
	v_mul_f32_dpp v24, v35, v17 row_newbcast:0 row_mask:0xf bank_mask:0xf bound_ctrl:1
	v_mul_f32_dpp v25, v35, v16 row_newbcast:1 row_mask:0xf bank_mask:0xf bound_ctrl:1
	v_fmac_f32_dpp v24, v35, v15 row_newbcast:2 row_mask:0xf bank_mask:0xf bound_ctrl:1
	v_fmac_f32_dpp v25, v35, v14 row_newbcast:3 row_mask:0xf bank_mask:0xf bound_ctrl:1
	v_fmac_f32_dpp v24, v35, v13 row_newbcast:4 row_mask:0xf bank_mask:0xf bound_ctrl:1
	v_fmac_f32_dpp v25, v35, v12 row_newbcast:5 row_mask:0xf bank_mask:0xf bound_ctrl:1
	v_fmac_f32_dpp v24, v35, v11 row_newbcast:6 row_mask:0xf bank_mask:0xf bound_ctrl:1
	v_fmac_f32_dpp v25, v35, v10 row_newbcast:7 row_mask:0xf bank_mask:0xf bound_ctrl:1
	s_nop 0
	v_fmac_f32_dpp v24, v35, v9 row_newbcast:8 row_mask:0xf bank_mask:0xf bound_ctrl:1
	v_fmac_f32_dpp v25, v35, v8 row_newbcast:9 row_mask:0xf bank_mask:0xf bound_ctrl:1
	v_fmac_f32_dpp v24, v35, v7 row_newbcast:10 row_mask:0xf bank_mask:0xf bound_ctrl:1
	v_fmac_f32_dpp v25, v35, v6 row_newbcast:11 row_mask:0xf bank_mask:0xf bound_ctrl:1
	s_nop 0
	v_fmac_f32_dpp v24, v35, v5 row_newbcast:12 row_mask:0xf bank_mask:0xf bound_ctrl:1
	v_fmac_f32_dpp v25, v35, v4 row_newbcast:13 row_mask:0xf bank_mask:0xf bound_ctrl:1
	v_fmac_f32_dpp v24, v35, v3 row_newbcast:14 row_mask:0xf bank_mask:0xf bound_ctrl:1
	v_fmac_f32_dpp v25, v35, v2 row_newbcast:15 row_mask:0xf bank_mask:0xf bound_ctrl:1
	s_waitcnt lgkmcnt(0)
	ds_read_b32 v34, v19 offset:21760
	ds_read2st64_b32 v[30:31], v21 offset0:21 offset1:37
	ds_read2st64_b32 v[32:33], v21 offset0:53 offset1:69
	v_mul_f32_dpp v35, v26, v17 row_newbcast:0 row_mask:0xf bank_mask:0xf bound_ctrl:1
	v_mul_f32_dpp v36, v26, v16 row_newbcast:1 row_mask:0xf bank_mask:0xf bound_ctrl:1
	v_fmac_f32_dpp v35, v26, v15 row_newbcast:2 row_mask:0xf bank_mask:0xf bound_ctrl:1
	v_fmac_f32_dpp v36, v26, v14 row_newbcast:3 row_mask:0xf bank_mask:0xf bound_ctrl:1
	v_fma_f32 v41, s94, v39, v224
	v_fmac_f32_dpp v35, v26, v13 row_newbcast:4 row_mask:0xf bank_mask:0xf bound_ctrl:1
	v_fmac_f32_dpp v36, v26, v12 row_newbcast:5 row_mask:0xf bank_mask:0xf bound_ctrl:1
	v_fmac_f32_dpp v35, v26, v11 row_newbcast:6 row_mask:0xf bank_mask:0xf bound_ctrl:1
	v_fmac_f32_dpp v36, v26, v10 row_newbcast:7 row_mask:0xf bank_mask:0xf bound_ctrl:1
	v_fmac_f32_e32 v41, s93, v37
	v_fmac_f32_dpp v35, v26, v9 row_newbcast:8 row_mask:0xf bank_mask:0xf bound_ctrl:1
	v_fmac_f32_dpp v36, v26, v8 row_newbcast:9 row_mask:0xf bank_mask:0xf bound_ctrl:1
	v_fmac_f32_dpp v35, v26, v7 row_newbcast:10 row_mask:0xf bank_mask:0xf bound_ctrl:1
	v_fmac_f32_dpp v36, v26, v6 row_newbcast:11 row_mask:0xf bank_mask:0xf bound_ctrl:1
	s_nop 0
	v_fmac_f32_dpp v35, v26, v5 row_newbcast:12 row_mask:0xf bank_mask:0xf bound_ctrl:1
	v_fmac_f32_dpp v36, v26, v4 row_newbcast:13 row_mask:0xf bank_mask:0xf bound_ctrl:1
	v_fmac_f32_dpp v35, v26, v3 row_newbcast:14 row_mask:0xf bank_mask:0xf bound_ctrl:1
	v_fmac_f32_dpp v36, v26, v2 row_newbcast:15 row_mask:0xf bank_mask:0xf bound_ctrl:1
	v_fmac_f32_dpp v17, v27, v41 row_newbcast:0 row_mask:0xf bank_mask:0xf bound_ctrl:1
	v_fmac_f32_dpp v16, v27, v41 row_newbcast:1 row_mask:0xf bank_mask:0xf bound_ctrl:1
	v_fmac_f32_dpp v15, v27, v41 row_newbcast:2 row_mask:0xf bank_mask:0xf bound_ctrl:1
	v_fmac_f32_dpp v14, v27, v41 row_newbcast:3 row_mask:0xf bank_mask:0xf bound_ctrl:1
	v_fmac_f32_dpp v13, v27, v41 row_newbcast:4 row_mask:0xf bank_mask:0xf bound_ctrl:1
	v_fmac_f32_dpp v12, v27, v41 row_newbcast:5 row_mask:0xf bank_mask:0xf bound_ctrl:1
	v_fmac_f32_dpp v11, v27, v41 row_newbcast:6 row_mask:0xf bank_mask:0xf bound_ctrl:1
	v_fmac_f32_dpp v10, v27, v41 row_newbcast:7 row_mask:0xf bank_mask:0xf bound_ctrl:1
	v_fmac_f32_dpp v9, v27, v41 row_newbcast:8 row_mask:0xf bank_mask:0xf bound_ctrl:1
	v_fmac_f32_dpp v8, v27, v41 row_newbcast:9 row_mask:0xf bank_mask:0xf bound_ctrl:1
	v_fmac_f32_dpp v7, v27, v41 row_newbcast:10 row_mask:0xf bank_mask:0xf bound_ctrl:1
	v_fmac_f32_dpp v6, v27, v41 row_newbcast:11 row_mask:0xf bank_mask:0xf bound_ctrl:1
	v_fmac_f32_dpp v5, v27, v41 row_newbcast:12 row_mask:0xf bank_mask:0xf bound_ctrl:1
	v_fmac_f32_dpp v4, v27, v41 row_newbcast:13 row_mask:0xf bank_mask:0xf bound_ctrl:1
	v_fmac_f32_dpp v3, v27, v41 row_newbcast:14 row_mask:0xf bank_mask:0xf bound_ctrl:1
	v_fmac_f32_dpp v2, v27, v41 row_newbcast:15 row_mask:0xf bank_mask:0xf bound_ctrl:1
	s_nop 0
	v_add_f32 v35, v35, v36
	s_nop 0
	s_nop 0
	v_mfma_f32_16x16x4_f32 v[224:227], v228, v35, 0
	ds_write_b64 v22, v[24:25] offset:55296
	v_fmac_f32_dpp v17, v28, v40 row_newbcast:0 row_mask:0xf bank_mask:0xf bound_ctrl:1
	v_fmac_f32_dpp v16, v28, v40 row_newbcast:1 row_mask:0xf bank_mask:0xf bound_ctrl:1
	v_fmac_f32_dpp v15, v28, v40 row_newbcast:2 row_mask:0xf bank_mask:0xf bound_ctrl:1
	v_fmac_f32_dpp v14, v28, v40 row_newbcast:3 row_mask:0xf bank_mask:0xf bound_ctrl:1
	v_fmac_f32_dpp v13, v28, v40 row_newbcast:4 row_mask:0xf bank_mask:0xf bound_ctrl:1
	v_fmac_f32_dpp v12, v28, v40 row_newbcast:5 row_mask:0xf bank_mask:0xf bound_ctrl:1
	v_fmac_f32_dpp v11, v28, v40 row_newbcast:6 row_mask:0xf bank_mask:0xf bound_ctrl:1
	v_fmac_f32_dpp v10, v28, v40 row_newbcast:7 row_mask:0xf bank_mask:0xf bound_ctrl:1
	v_fmac_f32_dpp v9, v28, v40 row_newbcast:8 row_mask:0xf bank_mask:0xf bound_ctrl:1
	v_fmac_f32_dpp v8, v28, v40 row_newbcast:9 row_mask:0xf bank_mask:0xf bound_ctrl:1
	v_fmac_f32_dpp v7, v28, v40 row_newbcast:10 row_mask:0xf bank_mask:0xf bound_ctrl:1
	v_fmac_f32_dpp v6, v28, v40 row_newbcast:11 row_mask:0xf bank_mask:0xf bound_ctrl:1
	v_fmac_f32_dpp v5, v28, v40 row_newbcast:12 row_mask:0xf bank_mask:0xf bound_ctrl:1
	v_fmac_f32_dpp v4, v28, v40 row_newbcast:13 row_mask:0xf bank_mask:0xf bound_ctrl:1
	v_fmac_f32_dpp v3, v28, v40 row_newbcast:14 row_mask:0xf bank_mask:0xf bound_ctrl:1
	v_fmac_f32_dpp v2, v28, v40 row_newbcast:15 row_mask:0xf bank_mask:0xf bound_ctrl:1
	v_mul_f32_dpp v24, v29, v17 row_newbcast:0 row_mask:0xf bank_mask:0xf bound_ctrl:1
	v_mul_f32_dpp v25, v29, v16 row_newbcast:1 row_mask:0xf bank_mask:0xf bound_ctrl:1
	v_fmac_f32_dpp v24, v29, v15 row_newbcast:2 row_mask:0xf bank_mask:0xf bound_ctrl:1
	v_fmac_f32_dpp v25, v29, v14 row_newbcast:3 row_mask:0xf bank_mask:0xf bound_ctrl:1
	v_fmac_f32_dpp v24, v29, v13 row_newbcast:4 row_mask:0xf bank_mask:0xf bound_ctrl:1
	v_fmac_f32_dpp v25, v29, v12 row_newbcast:5 row_mask:0xf bank_mask:0xf bound_ctrl:1
	v_fmac_f32_dpp v24, v29, v11 row_newbcast:6 row_mask:0xf bank_mask:0xf bound_ctrl:1
	v_fmac_f32_dpp v25, v29, v10 row_newbcast:7 row_mask:0xf bank_mask:0xf bound_ctrl:1
	s_nop 0
	v_fmac_f32_dpp v24, v29, v9 row_newbcast:8 row_mask:0xf bank_mask:0xf bound_ctrl:1
	v_fmac_f32_dpp v25, v29, v8 row_newbcast:9 row_mask:0xf bank_mask:0xf bound_ctrl:1
	v_fmac_f32_dpp v24, v29, v7 row_newbcast:10 row_mask:0xf bank_mask:0xf bound_ctrl:1
	v_fmac_f32_dpp v25, v29, v6 row_newbcast:11 row_mask:0xf bank_mask:0xf bound_ctrl:1
	s_nop 0
	v_fmac_f32_dpp v24, v29, v5 row_newbcast:12 row_mask:0xf bank_mask:0xf bound_ctrl:1
	v_fmac_f32_dpp v25, v29, v4 row_newbcast:13 row_mask:0xf bank_mask:0xf bound_ctrl:1
	v_fmac_f32_dpp v24, v29, v3 row_newbcast:14 row_mask:0xf bank_mask:0xf bound_ctrl:1
	v_fmac_f32_dpp v25, v29, v2 row_newbcast:15 row_mask:0xf bank_mask:0xf bound_ctrl:1
	s_waitcnt lgkmcnt(0)
	ds_read_b32 v36, v19 offset:22016
	ds_read2st64_b32 v[26:27], v21 offset0:22 offset1:38
	ds_read2st64_b32 v[28:29], v21 offset0:54 offset1:70
	v_mul_f32_dpp v37, v30, v17 row_newbcast:0 row_mask:0xf bank_mask:0xf bound_ctrl:1
	v_mul_f32_dpp v38, v30, v16 row_newbcast:1 row_mask:0xf bank_mask:0xf bound_ctrl:1
	v_fmac_f32_dpp v37, v30, v15 row_newbcast:2 row_mask:0xf bank_mask:0xf bound_ctrl:1
	v_fmac_f32_dpp v38, v30, v14 row_newbcast:3 row_mask:0xf bank_mask:0xf bound_ctrl:1
	v_fma_f32 v35, s92, v41, v224
	v_fmac_f32_dpp v37, v30, v13 row_newbcast:4 row_mask:0xf bank_mask:0xf bound_ctrl:1
	v_fmac_f32_dpp v38, v30, v12 row_newbcast:5 row_mask:0xf bank_mask:0xf bound_ctrl:1
	v_fmac_f32_dpp v37, v30, v11 row_newbcast:6 row_mask:0xf bank_mask:0xf bound_ctrl:1
	v_fmac_f32_dpp v38, v30, v10 row_newbcast:7 row_mask:0xf bank_mask:0xf bound_ctrl:1
	v_fmac_f32_e32 v35, s91, v40
	v_fmac_f32_dpp v37, v30, v9 row_newbcast:8 row_mask:0xf bank_mask:0xf bound_ctrl:1
	v_fmac_f32_dpp v38, v30, v8 row_newbcast:9 row_mask:0xf bank_mask:0xf bound_ctrl:1
	v_fmac_f32_dpp v37, v30, v7 row_newbcast:10 row_mask:0xf bank_mask:0xf bound_ctrl:1
	v_fmac_f32_dpp v38, v30, v6 row_newbcast:11 row_mask:0xf bank_mask:0xf bound_ctrl:1
	s_nop 0
	v_fmac_f32_dpp v37, v30, v5 row_newbcast:12 row_mask:0xf bank_mask:0xf bound_ctrl:1
	v_fmac_f32_dpp v38, v30, v4 row_newbcast:13 row_mask:0xf bank_mask:0xf bound_ctrl:1
	v_fmac_f32_dpp v37, v30, v3 row_newbcast:14 row_mask:0xf bank_mask:0xf bound_ctrl:1
	v_fmac_f32_dpp v38, v30, v2 row_newbcast:15 row_mask:0xf bank_mask:0xf bound_ctrl:1
	v_fmac_f32_dpp v17, v31, v35 row_newbcast:0 row_mask:0xf bank_mask:0xf bound_ctrl:1
	v_fmac_f32_dpp v16, v31, v35 row_newbcast:1 row_mask:0xf bank_mask:0xf bound_ctrl:1
	v_fmac_f32_dpp v15, v31, v35 row_newbcast:2 row_mask:0xf bank_mask:0xf bound_ctrl:1
	v_fmac_f32_dpp v14, v31, v35 row_newbcast:3 row_mask:0xf bank_mask:0xf bound_ctrl:1
	v_fmac_f32_dpp v13, v31, v35 row_newbcast:4 row_mask:0xf bank_mask:0xf bound_ctrl:1
	v_fmac_f32_dpp v12, v31, v35 row_newbcast:5 row_mask:0xf bank_mask:0xf bound_ctrl:1
	v_fmac_f32_dpp v11, v31, v35 row_newbcast:6 row_mask:0xf bank_mask:0xf bound_ctrl:1
	v_fmac_f32_dpp v10, v31, v35 row_newbcast:7 row_mask:0xf bank_mask:0xf bound_ctrl:1
	v_fmac_f32_dpp v9, v31, v35 row_newbcast:8 row_mask:0xf bank_mask:0xf bound_ctrl:1
	v_fmac_f32_dpp v8, v31, v35 row_newbcast:9 row_mask:0xf bank_mask:0xf bound_ctrl:1
	v_fmac_f32_dpp v7, v31, v35 row_newbcast:10 row_mask:0xf bank_mask:0xf bound_ctrl:1
	v_fmac_f32_dpp v6, v31, v35 row_newbcast:11 row_mask:0xf bank_mask:0xf bound_ctrl:1
	v_fmac_f32_dpp v5, v31, v35 row_newbcast:12 row_mask:0xf bank_mask:0xf bound_ctrl:1
	v_fmac_f32_dpp v4, v31, v35 row_newbcast:13 row_mask:0xf bank_mask:0xf bound_ctrl:1
	v_fmac_f32_dpp v3, v31, v35 row_newbcast:14 row_mask:0xf bank_mask:0xf bound_ctrl:1
	v_fmac_f32_dpp v2, v31, v35 row_newbcast:15 row_mask:0xf bank_mask:0xf bound_ctrl:1
	s_nop 0
	v_add_f32 v37, v37, v38
	s_nop 0
	s_nop 0
	v_mfma_f32_16x16x4_f32 v[224:227], v228, v37, 0
	ds_write_b64 v22, v[24:25] offset:57344
	v_fmac_f32_dpp v17, v32, v34 row_newbcast:0 row_mask:0xf bank_mask:0xf bound_ctrl:1
	v_fmac_f32_dpp v16, v32, v34 row_newbcast:1 row_mask:0xf bank_mask:0xf bound_ctrl:1
	v_fmac_f32_dpp v15, v32, v34 row_newbcast:2 row_mask:0xf bank_mask:0xf bound_ctrl:1
	v_fmac_f32_dpp v14, v32, v34 row_newbcast:3 row_mask:0xf bank_mask:0xf bound_ctrl:1
	v_fmac_f32_dpp v13, v32, v34 row_newbcast:4 row_mask:0xf bank_mask:0xf bound_ctrl:1
	v_fmac_f32_dpp v12, v32, v34 row_newbcast:5 row_mask:0xf bank_mask:0xf bound_ctrl:1
	v_fmac_f32_dpp v11, v32, v34 row_newbcast:6 row_mask:0xf bank_mask:0xf bound_ctrl:1
	v_fmac_f32_dpp v10, v32, v34 row_newbcast:7 row_mask:0xf bank_mask:0xf bound_ctrl:1
	v_fmac_f32_dpp v9, v32, v34 row_newbcast:8 row_mask:0xf bank_mask:0xf bound_ctrl:1
	v_fmac_f32_dpp v8, v32, v34 row_newbcast:9 row_mask:0xf bank_mask:0xf bound_ctrl:1
	v_fmac_f32_dpp v7, v32, v34 row_newbcast:10 row_mask:0xf bank_mask:0xf bound_ctrl:1
	v_fmac_f32_dpp v6, v32, v34 row_newbcast:11 row_mask:0xf bank_mask:0xf bound_ctrl:1
	v_fmac_f32_dpp v5, v32, v34 row_newbcast:12 row_mask:0xf bank_mask:0xf bound_ctrl:1
	v_fmac_f32_dpp v4, v32, v34 row_newbcast:13 row_mask:0xf bank_mask:0xf bound_ctrl:1
	v_fmac_f32_dpp v3, v32, v34 row_newbcast:14 row_mask:0xf bank_mask:0xf bound_ctrl:1
	v_fmac_f32_dpp v2, v32, v34 row_newbcast:15 row_mask:0xf bank_mask:0xf bound_ctrl:1
	v_mul_f32_dpp v24, v33, v17 row_newbcast:0 row_mask:0xf bank_mask:0xf bound_ctrl:1
	v_mul_f32_dpp v25, v33, v16 row_newbcast:1 row_mask:0xf bank_mask:0xf bound_ctrl:1
	v_fmac_f32_dpp v24, v33, v15 row_newbcast:2 row_mask:0xf bank_mask:0xf bound_ctrl:1
	v_fmac_f32_dpp v25, v33, v14 row_newbcast:3 row_mask:0xf bank_mask:0xf bound_ctrl:1
	v_fmac_f32_dpp v24, v33, v13 row_newbcast:4 row_mask:0xf bank_mask:0xf bound_ctrl:1
	v_fmac_f32_dpp v25, v33, v12 row_newbcast:5 row_mask:0xf bank_mask:0xf bound_ctrl:1
	v_fmac_f32_dpp v24, v33, v11 row_newbcast:6 row_mask:0xf bank_mask:0xf bound_ctrl:1
	v_fmac_f32_dpp v25, v33, v10 row_newbcast:7 row_mask:0xf bank_mask:0xf bound_ctrl:1
	s_nop 0
	v_fmac_f32_dpp v24, v33, v9 row_newbcast:8 row_mask:0xf bank_mask:0xf bound_ctrl:1
	v_fmac_f32_dpp v25, v33, v8 row_newbcast:9 row_mask:0xf bank_mask:0xf bound_ctrl:1
	v_fmac_f32_dpp v24, v33, v7 row_newbcast:10 row_mask:0xf bank_mask:0xf bound_ctrl:1
	v_fmac_f32_dpp v25, v33, v6 row_newbcast:11 row_mask:0xf bank_mask:0xf bound_ctrl:1
	s_nop 0
	v_fmac_f32_dpp v24, v33, v5 row_newbcast:12 row_mask:0xf bank_mask:0xf bound_ctrl:1
	v_fmac_f32_dpp v25, v33, v4 row_newbcast:13 row_mask:0xf bank_mask:0xf bound_ctrl:1
	v_fmac_f32_dpp v24, v33, v3 row_newbcast:14 row_mask:0xf bank_mask:0xf bound_ctrl:1
	v_fmac_f32_dpp v25, v33, v2 row_newbcast:15 row_mask:0xf bank_mask:0xf bound_ctrl:1
	s_waitcnt lgkmcnt(0)
	ds_read_b32 v38, v19 offset:22272
	ds_read2st64_b32 v[30:31], v21 offset0:23 offset1:39
	ds_read2st64_b32 v[32:33], v21 offset0:55 offset1:71
	v_mul_f32_dpp v39, v26, v17 row_newbcast:0 row_mask:0xf bank_mask:0xf bound_ctrl:1
	v_mul_f32_dpp v40, v26, v16 row_newbcast:1 row_mask:0xf bank_mask:0xf bound_ctrl:1
	v_fmac_f32_dpp v39, v26, v15 row_newbcast:2 row_mask:0xf bank_mask:0xf bound_ctrl:1
	v_fmac_f32_dpp v40, v26, v14 row_newbcast:3 row_mask:0xf bank_mask:0xf bound_ctrl:1
	v_fma_f32 v37, s90, v35, v224
	v_fmac_f32_dpp v39, v26, v13 row_newbcast:4 row_mask:0xf bank_mask:0xf bound_ctrl:1
	v_fmac_f32_dpp v40, v26, v12 row_newbcast:5 row_mask:0xf bank_mask:0xf bound_ctrl:1
	v_fmac_f32_dpp v39, v26, v11 row_newbcast:6 row_mask:0xf bank_mask:0xf bound_ctrl:1
	v_fmac_f32_dpp v40, v26, v10 row_newbcast:7 row_mask:0xf bank_mask:0xf bound_ctrl:1
	v_fmac_f32_e32 v37, s89, v34
	v_fmac_f32_dpp v39, v26, v9 row_newbcast:8 row_mask:0xf bank_mask:0xf bound_ctrl:1
	v_fmac_f32_dpp v40, v26, v8 row_newbcast:9 row_mask:0xf bank_mask:0xf bound_ctrl:1
	v_fmac_f32_dpp v39, v26, v7 row_newbcast:10 row_mask:0xf bank_mask:0xf bound_ctrl:1
	v_fmac_f32_dpp v40, v26, v6 row_newbcast:11 row_mask:0xf bank_mask:0xf bound_ctrl:1
	s_nop 0
	v_fmac_f32_dpp v39, v26, v5 row_newbcast:12 row_mask:0xf bank_mask:0xf bound_ctrl:1
	v_fmac_f32_dpp v40, v26, v4 row_newbcast:13 row_mask:0xf bank_mask:0xf bound_ctrl:1
	v_fmac_f32_dpp v39, v26, v3 row_newbcast:14 row_mask:0xf bank_mask:0xf bound_ctrl:1
	v_fmac_f32_dpp v40, v26, v2 row_newbcast:15 row_mask:0xf bank_mask:0xf bound_ctrl:1
	v_fmac_f32_dpp v17, v27, v37 row_newbcast:0 row_mask:0xf bank_mask:0xf bound_ctrl:1
	v_fmac_f32_dpp v16, v27, v37 row_newbcast:1 row_mask:0xf bank_mask:0xf bound_ctrl:1
	v_fmac_f32_dpp v15, v27, v37 row_newbcast:2 row_mask:0xf bank_mask:0xf bound_ctrl:1
	v_fmac_f32_dpp v14, v27, v37 row_newbcast:3 row_mask:0xf bank_mask:0xf bound_ctrl:1
	v_fmac_f32_dpp v13, v27, v37 row_newbcast:4 row_mask:0xf bank_mask:0xf bound_ctrl:1
	v_fmac_f32_dpp v12, v27, v37 row_newbcast:5 row_mask:0xf bank_mask:0xf bound_ctrl:1
	v_fmac_f32_dpp v11, v27, v37 row_newbcast:6 row_mask:0xf bank_mask:0xf bound_ctrl:1
	v_fmac_f32_dpp v10, v27, v37 row_newbcast:7 row_mask:0xf bank_mask:0xf bound_ctrl:1
	v_fmac_f32_dpp v9, v27, v37 row_newbcast:8 row_mask:0xf bank_mask:0xf bound_ctrl:1
	v_fmac_f32_dpp v8, v27, v37 row_newbcast:9 row_mask:0xf bank_mask:0xf bound_ctrl:1
	v_fmac_f32_dpp v7, v27, v37 row_newbcast:10 row_mask:0xf bank_mask:0xf bound_ctrl:1
	v_fmac_f32_dpp v6, v27, v37 row_newbcast:11 row_mask:0xf bank_mask:0xf bound_ctrl:1
	v_fmac_f32_dpp v5, v27, v37 row_newbcast:12 row_mask:0xf bank_mask:0xf bound_ctrl:1
	v_fmac_f32_dpp v4, v27, v37 row_newbcast:13 row_mask:0xf bank_mask:0xf bound_ctrl:1
	v_fmac_f32_dpp v3, v27, v37 row_newbcast:14 row_mask:0xf bank_mask:0xf bound_ctrl:1
	v_fmac_f32_dpp v2, v27, v37 row_newbcast:15 row_mask:0xf bank_mask:0xf bound_ctrl:1
	s_nop 0
	v_add_f32 v39, v39, v40
	s_nop 0
	s_nop 0
	v_mfma_f32_16x16x4_f32 v[224:227], v228, v39, 0
	ds_write_b64 v22, v[24:25] offset:59392
	v_fmac_f32_dpp v17, v28, v36 row_newbcast:0 row_mask:0xf bank_mask:0xf bound_ctrl:1
	v_fmac_f32_dpp v16, v28, v36 row_newbcast:1 row_mask:0xf bank_mask:0xf bound_ctrl:1
	v_fmac_f32_dpp v15, v28, v36 row_newbcast:2 row_mask:0xf bank_mask:0xf bound_ctrl:1
	v_fmac_f32_dpp v14, v28, v36 row_newbcast:3 row_mask:0xf bank_mask:0xf bound_ctrl:1
	v_fmac_f32_dpp v13, v28, v36 row_newbcast:4 row_mask:0xf bank_mask:0xf bound_ctrl:1
	v_fmac_f32_dpp v12, v28, v36 row_newbcast:5 row_mask:0xf bank_mask:0xf bound_ctrl:1
	v_fmac_f32_dpp v11, v28, v36 row_newbcast:6 row_mask:0xf bank_mask:0xf bound_ctrl:1
	v_fmac_f32_dpp v10, v28, v36 row_newbcast:7 row_mask:0xf bank_mask:0xf bound_ctrl:1
	v_fmac_f32_dpp v9, v28, v36 row_newbcast:8 row_mask:0xf bank_mask:0xf bound_ctrl:1
	v_fmac_f32_dpp v8, v28, v36 row_newbcast:9 row_mask:0xf bank_mask:0xf bound_ctrl:1
	v_fmac_f32_dpp v7, v28, v36 row_newbcast:10 row_mask:0xf bank_mask:0xf bound_ctrl:1
	v_fmac_f32_dpp v6, v28, v36 row_newbcast:11 row_mask:0xf bank_mask:0xf bound_ctrl:1
	v_fmac_f32_dpp v5, v28, v36 row_newbcast:12 row_mask:0xf bank_mask:0xf bound_ctrl:1
	v_fmac_f32_dpp v4, v28, v36 row_newbcast:13 row_mask:0xf bank_mask:0xf bound_ctrl:1
	v_fmac_f32_dpp v3, v28, v36 row_newbcast:14 row_mask:0xf bank_mask:0xf bound_ctrl:1
	v_fmac_f32_dpp v2, v28, v36 row_newbcast:15 row_mask:0xf bank_mask:0xf bound_ctrl:1
	v_mul_f32_dpp v24, v29, v17 row_newbcast:0 row_mask:0xf bank_mask:0xf bound_ctrl:1
	v_mul_f32_dpp v25, v29, v16 row_newbcast:1 row_mask:0xf bank_mask:0xf bound_ctrl:1
	v_fmac_f32_dpp v24, v29, v15 row_newbcast:2 row_mask:0xf bank_mask:0xf bound_ctrl:1
	v_fmac_f32_dpp v25, v29, v14 row_newbcast:3 row_mask:0xf bank_mask:0xf bound_ctrl:1
	v_fmac_f32_dpp v24, v29, v13 row_newbcast:4 row_mask:0xf bank_mask:0xf bound_ctrl:1
	v_fmac_f32_dpp v25, v29, v12 row_newbcast:5 row_mask:0xf bank_mask:0xf bound_ctrl:1
	v_fmac_f32_dpp v24, v29, v11 row_newbcast:6 row_mask:0xf bank_mask:0xf bound_ctrl:1
	v_fmac_f32_dpp v25, v29, v10 row_newbcast:7 row_mask:0xf bank_mask:0xf bound_ctrl:1
	s_nop 0
	v_fmac_f32_dpp v24, v29, v9 row_newbcast:8 row_mask:0xf bank_mask:0xf bound_ctrl:1
	v_fmac_f32_dpp v25, v29, v8 row_newbcast:9 row_mask:0xf bank_mask:0xf bound_ctrl:1
	v_fmac_f32_dpp v24, v29, v7 row_newbcast:10 row_mask:0xf bank_mask:0xf bound_ctrl:1
	v_fmac_f32_dpp v25, v29, v6 row_newbcast:11 row_mask:0xf bank_mask:0xf bound_ctrl:1
	s_nop 0
	v_fmac_f32_dpp v24, v29, v5 row_newbcast:12 row_mask:0xf bank_mask:0xf bound_ctrl:1
	v_fmac_f32_dpp v25, v29, v4 row_newbcast:13 row_mask:0xf bank_mask:0xf bound_ctrl:1
	v_fmac_f32_dpp v24, v29, v3 row_newbcast:14 row_mask:0xf bank_mask:0xf bound_ctrl:1
	v_fmac_f32_dpp v25, v29, v2 row_newbcast:15 row_mask:0xf bank_mask:0xf bound_ctrl:1
	s_waitcnt lgkmcnt(0)
	ds_read_b32 v34, v19 offset:22528
	ds_read2st64_b32 v[26:27], v21 offset0:24 offset1:40
	ds_read2st64_b32 v[28:29], v21 offset0:56 offset1:72
	v_mul_f32_dpp v35, v30, v17 row_newbcast:0 row_mask:0xf bank_mask:0xf bound_ctrl:1
	v_mul_f32_dpp v40, v30, v16 row_newbcast:1 row_mask:0xf bank_mask:0xf bound_ctrl:1
	v_fmac_f32_dpp v35, v30, v15 row_newbcast:2 row_mask:0xf bank_mask:0xf bound_ctrl:1
	v_fmac_f32_dpp v40, v30, v14 row_newbcast:3 row_mask:0xf bank_mask:0xf bound_ctrl:1
	v_fma_f32 v39, s88, v37, v224
	v_fmac_f32_dpp v35, v30, v13 row_newbcast:4 row_mask:0xf bank_mask:0xf bound_ctrl:1
	v_fmac_f32_dpp v40, v30, v12 row_newbcast:5 row_mask:0xf bank_mask:0xf bound_ctrl:1
	v_fmac_f32_dpp v35, v30, v11 row_newbcast:6 row_mask:0xf bank_mask:0xf bound_ctrl:1
	v_fmac_f32_dpp v40, v30, v10 row_newbcast:7 row_mask:0xf bank_mask:0xf bound_ctrl:1
	v_fmac_f32_e32 v39, s83, v36
	v_fmac_f32_dpp v35, v30, v9 row_newbcast:8 row_mask:0xf bank_mask:0xf bound_ctrl:1
	v_fmac_f32_dpp v40, v30, v8 row_newbcast:9 row_mask:0xf bank_mask:0xf bound_ctrl:1
	v_fmac_f32_dpp v35, v30, v7 row_newbcast:10 row_mask:0xf bank_mask:0xf bound_ctrl:1
	v_fmac_f32_dpp v40, v30, v6 row_newbcast:11 row_mask:0xf bank_mask:0xf bound_ctrl:1
	s_nop 0
	v_fmac_f32_dpp v35, v30, v5 row_newbcast:12 row_mask:0xf bank_mask:0xf bound_ctrl:1
	v_fmac_f32_dpp v40, v30, v4 row_newbcast:13 row_mask:0xf bank_mask:0xf bound_ctrl:1
	v_fmac_f32_dpp v35, v30, v3 row_newbcast:14 row_mask:0xf bank_mask:0xf bound_ctrl:1
	v_fmac_f32_dpp v40, v30, v2 row_newbcast:15 row_mask:0xf bank_mask:0xf bound_ctrl:1
	v_fmac_f32_dpp v17, v31, v39 row_newbcast:0 row_mask:0xf bank_mask:0xf bound_ctrl:1
	v_fmac_f32_dpp v16, v31, v39 row_newbcast:1 row_mask:0xf bank_mask:0xf bound_ctrl:1
	v_fmac_f32_dpp v15, v31, v39 row_newbcast:2 row_mask:0xf bank_mask:0xf bound_ctrl:1
	v_fmac_f32_dpp v14, v31, v39 row_newbcast:3 row_mask:0xf bank_mask:0xf bound_ctrl:1
	v_fmac_f32_dpp v13, v31, v39 row_newbcast:4 row_mask:0xf bank_mask:0xf bound_ctrl:1
	v_fmac_f32_dpp v12, v31, v39 row_newbcast:5 row_mask:0xf bank_mask:0xf bound_ctrl:1
	v_fmac_f32_dpp v11, v31, v39 row_newbcast:6 row_mask:0xf bank_mask:0xf bound_ctrl:1
	v_fmac_f32_dpp v10, v31, v39 row_newbcast:7 row_mask:0xf bank_mask:0xf bound_ctrl:1
	v_fmac_f32_dpp v9, v31, v39 row_newbcast:8 row_mask:0xf bank_mask:0xf bound_ctrl:1
	v_fmac_f32_dpp v8, v31, v39 row_newbcast:9 row_mask:0xf bank_mask:0xf bound_ctrl:1
	v_fmac_f32_dpp v7, v31, v39 row_newbcast:10 row_mask:0xf bank_mask:0xf bound_ctrl:1
	v_fmac_f32_dpp v6, v31, v39 row_newbcast:11 row_mask:0xf bank_mask:0xf bound_ctrl:1
	v_fmac_f32_dpp v5, v31, v39 row_newbcast:12 row_mask:0xf bank_mask:0xf bound_ctrl:1
	v_fmac_f32_dpp v4, v31, v39 row_newbcast:13 row_mask:0xf bank_mask:0xf bound_ctrl:1
	v_fmac_f32_dpp v3, v31, v39 row_newbcast:14 row_mask:0xf bank_mask:0xf bound_ctrl:1
	v_fmac_f32_dpp v2, v31, v39 row_newbcast:15 row_mask:0xf bank_mask:0xf bound_ctrl:1
	s_nop 0
	v_add_f32 v35, v35, v40
	s_nop 0
	s_nop 0
	v_mfma_f32_16x16x4_f32 v[224:227], v228, v35, 0
	ds_write_b64 v22, v[24:25] offset:61440
	v_fmac_f32_dpp v17, v32, v38 row_newbcast:0 row_mask:0xf bank_mask:0xf bound_ctrl:1
	v_fmac_f32_dpp v16, v32, v38 row_newbcast:1 row_mask:0xf bank_mask:0xf bound_ctrl:1
	v_fmac_f32_dpp v15, v32, v38 row_newbcast:2 row_mask:0xf bank_mask:0xf bound_ctrl:1
	v_fmac_f32_dpp v14, v32, v38 row_newbcast:3 row_mask:0xf bank_mask:0xf bound_ctrl:1
	v_fmac_f32_dpp v13, v32, v38 row_newbcast:4 row_mask:0xf bank_mask:0xf bound_ctrl:1
	v_fmac_f32_dpp v12, v32, v38 row_newbcast:5 row_mask:0xf bank_mask:0xf bound_ctrl:1
	v_fmac_f32_dpp v11, v32, v38 row_newbcast:6 row_mask:0xf bank_mask:0xf bound_ctrl:1
	v_fmac_f32_dpp v10, v32, v38 row_newbcast:7 row_mask:0xf bank_mask:0xf bound_ctrl:1
	v_fmac_f32_dpp v9, v32, v38 row_newbcast:8 row_mask:0xf bank_mask:0xf bound_ctrl:1
	v_fmac_f32_dpp v8, v32, v38 row_newbcast:9 row_mask:0xf bank_mask:0xf bound_ctrl:1
	v_fmac_f32_dpp v7, v32, v38 row_newbcast:10 row_mask:0xf bank_mask:0xf bound_ctrl:1
	v_fmac_f32_dpp v6, v32, v38 row_newbcast:11 row_mask:0xf bank_mask:0xf bound_ctrl:1
	v_fmac_f32_dpp v5, v32, v38 row_newbcast:12 row_mask:0xf bank_mask:0xf bound_ctrl:1
	v_fmac_f32_dpp v4, v32, v38 row_newbcast:13 row_mask:0xf bank_mask:0xf bound_ctrl:1
	v_fmac_f32_dpp v3, v32, v38 row_newbcast:14 row_mask:0xf bank_mask:0xf bound_ctrl:1
	v_fmac_f32_dpp v2, v32, v38 row_newbcast:15 row_mask:0xf bank_mask:0xf bound_ctrl:1
	v_mul_f32_dpp v24, v33, v17 row_newbcast:0 row_mask:0xf bank_mask:0xf bound_ctrl:1
	v_mul_f32_dpp v25, v33, v16 row_newbcast:1 row_mask:0xf bank_mask:0xf bound_ctrl:1
	v_fmac_f32_dpp v24, v33, v15 row_newbcast:2 row_mask:0xf bank_mask:0xf bound_ctrl:1
	v_fmac_f32_dpp v25, v33, v14 row_newbcast:3 row_mask:0xf bank_mask:0xf bound_ctrl:1
	v_fmac_f32_dpp v24, v33, v13 row_newbcast:4 row_mask:0xf bank_mask:0xf bound_ctrl:1
	v_fmac_f32_dpp v25, v33, v12 row_newbcast:5 row_mask:0xf bank_mask:0xf bound_ctrl:1
	v_fmac_f32_dpp v24, v33, v11 row_newbcast:6 row_mask:0xf bank_mask:0xf bound_ctrl:1
	v_fmac_f32_dpp v25, v33, v10 row_newbcast:7 row_mask:0xf bank_mask:0xf bound_ctrl:1
	s_nop 0
	v_fmac_f32_dpp v24, v33, v9 row_newbcast:8 row_mask:0xf bank_mask:0xf bound_ctrl:1
	v_fmac_f32_dpp v25, v33, v8 row_newbcast:9 row_mask:0xf bank_mask:0xf bound_ctrl:1
	v_fmac_f32_dpp v24, v33, v7 row_newbcast:10 row_mask:0xf bank_mask:0xf bound_ctrl:1
	v_fmac_f32_dpp v25, v33, v6 row_newbcast:11 row_mask:0xf bank_mask:0xf bound_ctrl:1
	s_nop 0
	v_fmac_f32_dpp v24, v33, v5 row_newbcast:12 row_mask:0xf bank_mask:0xf bound_ctrl:1
	v_fmac_f32_dpp v25, v33, v4 row_newbcast:13 row_mask:0xf bank_mask:0xf bound_ctrl:1
	v_fmac_f32_dpp v24, v33, v3 row_newbcast:14 row_mask:0xf bank_mask:0xf bound_ctrl:1
	v_fmac_f32_dpp v25, v33, v2 row_newbcast:15 row_mask:0xf bank_mask:0xf bound_ctrl:1
	s_waitcnt lgkmcnt(0)
	ds_read_b32 v36, v19 offset:22784
	ds_read2st64_b32 v[30:31], v21 offset0:25 offset1:41
	ds_read2st64_b32 v[32:33], v21 offset0:57 offset1:73
	v_mul_f32_dpp v37, v26, v17 row_newbcast:0 row_mask:0xf bank_mask:0xf bound_ctrl:1
	v_mul_f32_dpp v40, v26, v16 row_newbcast:1 row_mask:0xf bank_mask:0xf bound_ctrl:1
	v_fmac_f32_dpp v37, v26, v15 row_newbcast:2 row_mask:0xf bank_mask:0xf bound_ctrl:1
	v_fmac_f32_dpp v40, v26, v14 row_newbcast:3 row_mask:0xf bank_mask:0xf bound_ctrl:1
	v_fma_f32 v35, s82, v39, v224
	v_fmac_f32_dpp v37, v26, v13 row_newbcast:4 row_mask:0xf bank_mask:0xf bound_ctrl:1
	v_fmac_f32_dpp v40, v26, v12 row_newbcast:5 row_mask:0xf bank_mask:0xf bound_ctrl:1
	v_fmac_f32_dpp v37, v26, v11 row_newbcast:6 row_mask:0xf bank_mask:0xf bound_ctrl:1
	v_fmac_f32_dpp v40, v26, v10 row_newbcast:7 row_mask:0xf bank_mask:0xf bound_ctrl:1
	v_fmac_f32_e32 v35, s81, v38
	v_fmac_f32_dpp v37, v26, v9 row_newbcast:8 row_mask:0xf bank_mask:0xf bound_ctrl:1
	v_fmac_f32_dpp v40, v26, v8 row_newbcast:9 row_mask:0xf bank_mask:0xf bound_ctrl:1
	v_fmac_f32_dpp v37, v26, v7 row_newbcast:10 row_mask:0xf bank_mask:0xf bound_ctrl:1
	v_fmac_f32_dpp v40, v26, v6 row_newbcast:11 row_mask:0xf bank_mask:0xf bound_ctrl:1
	s_nop 0
	v_fmac_f32_dpp v37, v26, v5 row_newbcast:12 row_mask:0xf bank_mask:0xf bound_ctrl:1
	v_fmac_f32_dpp v40, v26, v4 row_newbcast:13 row_mask:0xf bank_mask:0xf bound_ctrl:1
	v_fmac_f32_dpp v37, v26, v3 row_newbcast:14 row_mask:0xf bank_mask:0xf bound_ctrl:1
	v_fmac_f32_dpp v40, v26, v2 row_newbcast:15 row_mask:0xf bank_mask:0xf bound_ctrl:1
	v_fmac_f32_dpp v17, v27, v35 row_newbcast:0 row_mask:0xf bank_mask:0xf bound_ctrl:1
	v_fmac_f32_dpp v16, v27, v35 row_newbcast:1 row_mask:0xf bank_mask:0xf bound_ctrl:1
	v_fmac_f32_dpp v15, v27, v35 row_newbcast:2 row_mask:0xf bank_mask:0xf bound_ctrl:1
	v_fmac_f32_dpp v14, v27, v35 row_newbcast:3 row_mask:0xf bank_mask:0xf bound_ctrl:1
	v_fmac_f32_dpp v13, v27, v35 row_newbcast:4 row_mask:0xf bank_mask:0xf bound_ctrl:1
	v_fmac_f32_dpp v12, v27, v35 row_newbcast:5 row_mask:0xf bank_mask:0xf bound_ctrl:1
	v_fmac_f32_dpp v11, v27, v35 row_newbcast:6 row_mask:0xf bank_mask:0xf bound_ctrl:1
	v_fmac_f32_dpp v10, v27, v35 row_newbcast:7 row_mask:0xf bank_mask:0xf bound_ctrl:1
	v_fmac_f32_dpp v9, v27, v35 row_newbcast:8 row_mask:0xf bank_mask:0xf bound_ctrl:1
	v_fmac_f32_dpp v8, v27, v35 row_newbcast:9 row_mask:0xf bank_mask:0xf bound_ctrl:1
	v_fmac_f32_dpp v7, v27, v35 row_newbcast:10 row_mask:0xf bank_mask:0xf bound_ctrl:1
	v_fmac_f32_dpp v6, v27, v35 row_newbcast:11 row_mask:0xf bank_mask:0xf bound_ctrl:1
	v_fmac_f32_dpp v5, v27, v35 row_newbcast:12 row_mask:0xf bank_mask:0xf bound_ctrl:1
	v_fmac_f32_dpp v4, v27, v35 row_newbcast:13 row_mask:0xf bank_mask:0xf bound_ctrl:1
	v_fmac_f32_dpp v3, v27, v35 row_newbcast:14 row_mask:0xf bank_mask:0xf bound_ctrl:1
	v_fmac_f32_dpp v2, v27, v35 row_newbcast:15 row_mask:0xf bank_mask:0xf bound_ctrl:1
	s_nop 0
	v_add_f32 v37, v37, v40
	s_nop 0
	s_nop 0
	v_mfma_f32_16x16x4_f32 v[224:227], v228, v37, 0
	ds_write_b64 v22, v[24:25] offset:63488
	v_fmac_f32_dpp v17, v28, v34 row_newbcast:0 row_mask:0xf bank_mask:0xf bound_ctrl:1
	v_fmac_f32_dpp v16, v28, v34 row_newbcast:1 row_mask:0xf bank_mask:0xf bound_ctrl:1
	v_fmac_f32_dpp v15, v28, v34 row_newbcast:2 row_mask:0xf bank_mask:0xf bound_ctrl:1
	v_fmac_f32_dpp v14, v28, v34 row_newbcast:3 row_mask:0xf bank_mask:0xf bound_ctrl:1
	v_fmac_f32_dpp v13, v28, v34 row_newbcast:4 row_mask:0xf bank_mask:0xf bound_ctrl:1
	v_fmac_f32_dpp v12, v28, v34 row_newbcast:5 row_mask:0xf bank_mask:0xf bound_ctrl:1
	v_fmac_f32_dpp v11, v28, v34 row_newbcast:6 row_mask:0xf bank_mask:0xf bound_ctrl:1
	v_fmac_f32_dpp v10, v28, v34 row_newbcast:7 row_mask:0xf bank_mask:0xf bound_ctrl:1
	v_fmac_f32_dpp v9, v28, v34 row_newbcast:8 row_mask:0xf bank_mask:0xf bound_ctrl:1
	v_fmac_f32_dpp v8, v28, v34 row_newbcast:9 row_mask:0xf bank_mask:0xf bound_ctrl:1
	v_fmac_f32_dpp v7, v28, v34 row_newbcast:10 row_mask:0xf bank_mask:0xf bound_ctrl:1
	v_fmac_f32_dpp v6, v28, v34 row_newbcast:11 row_mask:0xf bank_mask:0xf bound_ctrl:1
	v_fmac_f32_dpp v5, v28, v34 row_newbcast:12 row_mask:0xf bank_mask:0xf bound_ctrl:1
	v_fmac_f32_dpp v4, v28, v34 row_newbcast:13 row_mask:0xf bank_mask:0xf bound_ctrl:1
	v_fmac_f32_dpp v3, v28, v34 row_newbcast:14 row_mask:0xf bank_mask:0xf bound_ctrl:1
	v_fmac_f32_dpp v2, v28, v34 row_newbcast:15 row_mask:0xf bank_mask:0xf bound_ctrl:1
	v_mul_f32_dpp v22, v29, v17 row_newbcast:0 row_mask:0xf bank_mask:0xf bound_ctrl:1
	v_mul_f32_dpp v23, v29, v16 row_newbcast:1 row_mask:0xf bank_mask:0xf bound_ctrl:1
	v_fmac_f32_dpp v22, v29, v15 row_newbcast:2 row_mask:0xf bank_mask:0xf bound_ctrl:1
	v_fmac_f32_dpp v23, v29, v14 row_newbcast:3 row_mask:0xf bank_mask:0xf bound_ctrl:1
	v_fmac_f32_dpp v22, v29, v13 row_newbcast:4 row_mask:0xf bank_mask:0xf bound_ctrl:1
	v_fmac_f32_dpp v23, v29, v12 row_newbcast:5 row_mask:0xf bank_mask:0xf bound_ctrl:1
	v_fmac_f32_dpp v22, v29, v11 row_newbcast:6 row_mask:0xf bank_mask:0xf bound_ctrl:1
	v_fmac_f32_dpp v23, v29, v10 row_newbcast:7 row_mask:0xf bank_mask:0xf bound_ctrl:1
	s_nop 0
	v_fmac_f32_dpp v22, v29, v9 row_newbcast:8 row_mask:0xf bank_mask:0xf bound_ctrl:1
	v_fmac_f32_dpp v23, v29, v8 row_newbcast:9 row_mask:0xf bank_mask:0xf bound_ctrl:1
	v_fmac_f32_dpp v22, v29, v7 row_newbcast:10 row_mask:0xf bank_mask:0xf bound_ctrl:1
	v_fmac_f32_dpp v23, v29, v6 row_newbcast:11 row_mask:0xf bank_mask:0xf bound_ctrl:1
	s_nop 0
	v_fmac_f32_dpp v22, v29, v5 row_newbcast:12 row_mask:0xf bank_mask:0xf bound_ctrl:1
	v_fmac_f32_dpp v23, v29, v4 row_newbcast:13 row_mask:0xf bank_mask:0xf bound_ctrl:1
	v_fmac_f32_dpp v22, v29, v3 row_newbcast:14 row_mask:0xf bank_mask:0xf bound_ctrl:1
	v_fmac_f32_dpp v23, v29, v2 row_newbcast:15 row_mask:0xf bank_mask:0xf bound_ctrl:1
	s_waitcnt lgkmcnt(0)
	ds_read_b32 v38, v19 offset:23040
	ds_read2st64_b32 v[24:25], v21 offset0:26 offset1:42
	ds_read2st64_b32 v[26:27], v21 offset0:58 offset1:74
	v_mul_f32_dpp v39, v30, v17 row_newbcast:0 row_mask:0xf bank_mask:0xf bound_ctrl:1
	v_mul_f32_dpp v29, v30, v16 row_newbcast:1 row_mask:0xf bank_mask:0xf bound_ctrl:1
	v_fmac_f32_dpp v39, v30, v15 row_newbcast:2 row_mask:0xf bank_mask:0xf bound_ctrl:1
	v_fmac_f32_dpp v29, v30, v14 row_newbcast:3 row_mask:0xf bank_mask:0xf bound_ctrl:1
	v_fma_f32 v37, s80, v35, v224
	v_fmac_f32_dpp v39, v30, v13 row_newbcast:4 row_mask:0xf bank_mask:0xf bound_ctrl:1
	v_fmac_f32_dpp v29, v30, v12 row_newbcast:5 row_mask:0xf bank_mask:0xf bound_ctrl:1
	v_fmac_f32_dpp v39, v30, v11 row_newbcast:6 row_mask:0xf bank_mask:0xf bound_ctrl:1
	v_fmac_f32_dpp v29, v30, v10 row_newbcast:7 row_mask:0xf bank_mask:0xf bound_ctrl:1
	v_fmac_f32_e32 v37, s79, v34
	v_fmac_f32_dpp v39, v30, v9 row_newbcast:8 row_mask:0xf bank_mask:0xf bound_ctrl:1
	v_fmac_f32_dpp v29, v30, v8 row_newbcast:9 row_mask:0xf bank_mask:0xf bound_ctrl:1
	v_fmac_f32_dpp v39, v30, v7 row_newbcast:10 row_mask:0xf bank_mask:0xf bound_ctrl:1
	v_fmac_f32_dpp v29, v30, v6 row_newbcast:11 row_mask:0xf bank_mask:0xf bound_ctrl:1
	s_nop 0
	v_fmac_f32_dpp v39, v30, v5 row_newbcast:12 row_mask:0xf bank_mask:0xf bound_ctrl:1
	v_fmac_f32_dpp v29, v30, v4 row_newbcast:13 row_mask:0xf bank_mask:0xf bound_ctrl:1
	v_fmac_f32_dpp v39, v30, v3 row_newbcast:14 row_mask:0xf bank_mask:0xf bound_ctrl:1
	v_fmac_f32_dpp v29, v30, v2 row_newbcast:15 row_mask:0xf bank_mask:0xf bound_ctrl:1
	v_fmac_f32_dpp v17, v31, v37 row_newbcast:0 row_mask:0xf bank_mask:0xf bound_ctrl:1
	v_fmac_f32_dpp v16, v31, v37 row_newbcast:1 row_mask:0xf bank_mask:0xf bound_ctrl:1
	v_fmac_f32_dpp v15, v31, v37 row_newbcast:2 row_mask:0xf bank_mask:0xf bound_ctrl:1
	v_fmac_f32_dpp v14, v31, v37 row_newbcast:3 row_mask:0xf bank_mask:0xf bound_ctrl:1
	v_fmac_f32_dpp v13, v31, v37 row_newbcast:4 row_mask:0xf bank_mask:0xf bound_ctrl:1
	v_fmac_f32_dpp v12, v31, v37 row_newbcast:5 row_mask:0xf bank_mask:0xf bound_ctrl:1
	v_fmac_f32_dpp v11, v31, v37 row_newbcast:6 row_mask:0xf bank_mask:0xf bound_ctrl:1
	v_fmac_f32_dpp v10, v31, v37 row_newbcast:7 row_mask:0xf bank_mask:0xf bound_ctrl:1
	v_fmac_f32_dpp v9, v31, v37 row_newbcast:8 row_mask:0xf bank_mask:0xf bound_ctrl:1
	v_fmac_f32_dpp v8, v31, v37 row_newbcast:9 row_mask:0xf bank_mask:0xf bound_ctrl:1
	v_fmac_f32_dpp v7, v31, v37 row_newbcast:10 row_mask:0xf bank_mask:0xf bound_ctrl:1
	v_fmac_f32_dpp v6, v31, v37 row_newbcast:11 row_mask:0xf bank_mask:0xf bound_ctrl:1
	v_fmac_f32_dpp v5, v31, v37 row_newbcast:12 row_mask:0xf bank_mask:0xf bound_ctrl:1
	v_fmac_f32_dpp v4, v31, v37 row_newbcast:13 row_mask:0xf bank_mask:0xf bound_ctrl:1
	v_fmac_f32_dpp v3, v31, v37 row_newbcast:14 row_mask:0xf bank_mask:0xf bound_ctrl:1
	v_fmac_f32_dpp v2, v31, v37 row_newbcast:15 row_mask:0xf bank_mask:0xf bound_ctrl:1
	s_nop 0
	v_add_f32 v39, v39, v29
	s_nop 0
	s_nop 0
	v_mfma_f32_16x16x4_f32 v[224:227], v228, v39, 0
	ds_write_b64 v20, v[22:23] offset:16384
	v_fmac_f32_dpp v17, v32, v36 row_newbcast:0 row_mask:0xf bank_mask:0xf bound_ctrl:1
	v_fmac_f32_dpp v16, v32, v36 row_newbcast:1 row_mask:0xf bank_mask:0xf bound_ctrl:1
	v_fmac_f32_dpp v15, v32, v36 row_newbcast:2 row_mask:0xf bank_mask:0xf bound_ctrl:1
	v_fmac_f32_dpp v14, v32, v36 row_newbcast:3 row_mask:0xf bank_mask:0xf bound_ctrl:1
	v_fmac_f32_dpp v13, v32, v36 row_newbcast:4 row_mask:0xf bank_mask:0xf bound_ctrl:1
	v_fmac_f32_dpp v12, v32, v36 row_newbcast:5 row_mask:0xf bank_mask:0xf bound_ctrl:1
	v_fmac_f32_dpp v11, v32, v36 row_newbcast:6 row_mask:0xf bank_mask:0xf bound_ctrl:1
	v_fmac_f32_dpp v10, v32, v36 row_newbcast:7 row_mask:0xf bank_mask:0xf bound_ctrl:1
	v_fmac_f32_dpp v9, v32, v36 row_newbcast:8 row_mask:0xf bank_mask:0xf bound_ctrl:1
	v_fmac_f32_dpp v8, v32, v36 row_newbcast:9 row_mask:0xf bank_mask:0xf bound_ctrl:1
	v_fmac_f32_dpp v7, v32, v36 row_newbcast:10 row_mask:0xf bank_mask:0xf bound_ctrl:1
	v_fmac_f32_dpp v6, v32, v36 row_newbcast:11 row_mask:0xf bank_mask:0xf bound_ctrl:1
	v_fmac_f32_dpp v5, v32, v36 row_newbcast:12 row_mask:0xf bank_mask:0xf bound_ctrl:1
	v_fmac_f32_dpp v4, v32, v36 row_newbcast:13 row_mask:0xf bank_mask:0xf bound_ctrl:1
	v_fmac_f32_dpp v3, v32, v36 row_newbcast:14 row_mask:0xf bank_mask:0xf bound_ctrl:1
	v_fmac_f32_dpp v2, v32, v36 row_newbcast:15 row_mask:0xf bank_mask:0xf bound_ctrl:1
	v_mul_f32_dpp v22, v33, v17 row_newbcast:0 row_mask:0xf bank_mask:0xf bound_ctrl:1
	v_mul_f32_dpp v23, v33, v16 row_newbcast:1 row_mask:0xf bank_mask:0xf bound_ctrl:1
	v_fmac_f32_dpp v22, v33, v15 row_newbcast:2 row_mask:0xf bank_mask:0xf bound_ctrl:1
	v_fmac_f32_dpp v23, v33, v14 row_newbcast:3 row_mask:0xf bank_mask:0xf bound_ctrl:1
	v_fmac_f32_dpp v22, v33, v13 row_newbcast:4 row_mask:0xf bank_mask:0xf bound_ctrl:1
	v_fmac_f32_dpp v23, v33, v12 row_newbcast:5 row_mask:0xf bank_mask:0xf bound_ctrl:1
	v_fmac_f32_dpp v22, v33, v11 row_newbcast:6 row_mask:0xf bank_mask:0xf bound_ctrl:1
	v_fmac_f32_dpp v23, v33, v10 row_newbcast:7 row_mask:0xf bank_mask:0xf bound_ctrl:1
	s_nop 0
	v_fmac_f32_dpp v22, v33, v9 row_newbcast:8 row_mask:0xf bank_mask:0xf bound_ctrl:1
	v_fmac_f32_dpp v23, v33, v8 row_newbcast:9 row_mask:0xf bank_mask:0xf bound_ctrl:1
	v_fmac_f32_dpp v22, v33, v7 row_newbcast:10 row_mask:0xf bank_mask:0xf bound_ctrl:1
	v_fmac_f32_dpp v23, v33, v6 row_newbcast:11 row_mask:0xf bank_mask:0xf bound_ctrl:1
	s_nop 0
	v_fmac_f32_dpp v22, v33, v5 row_newbcast:12 row_mask:0xf bank_mask:0xf bound_ctrl:1
	v_fmac_f32_dpp v23, v33, v4 row_newbcast:13 row_mask:0xf bank_mask:0xf bound_ctrl:1
	v_fmac_f32_dpp v22, v33, v3 row_newbcast:14 row_mask:0xf bank_mask:0xf bound_ctrl:1
	v_fmac_f32_dpp v23, v33, v2 row_newbcast:15 row_mask:0xf bank_mask:0xf bound_ctrl:1
	s_waitcnt lgkmcnt(0)
	ds_read_b32 v33, v19 offset:23296
	ds_read2st64_b32 v[28:29], v21 offset0:27 offset1:43
	ds_read2st64_b32 v[30:31], v21 offset0:59 offset1:75
	v_mul_f32_dpp v34, v24, v17 row_newbcast:0 row_mask:0xf bank_mask:0xf bound_ctrl:1
	v_mul_f32_dpp v35, v24, v16 row_newbcast:1 row_mask:0xf bank_mask:0xf bound_ctrl:1
	v_fmac_f32_dpp v34, v24, v15 row_newbcast:2 row_mask:0xf bank_mask:0xf bound_ctrl:1
	v_fmac_f32_dpp v35, v24, v14 row_newbcast:3 row_mask:0xf bank_mask:0xf bound_ctrl:1
	v_fma_f32 v39, s67, v37, v224
	v_fmac_f32_dpp v34, v24, v13 row_newbcast:4 row_mask:0xf bank_mask:0xf bound_ctrl:1
	v_fmac_f32_dpp v35, v24, v12 row_newbcast:5 row_mask:0xf bank_mask:0xf bound_ctrl:1
	v_fmac_f32_dpp v34, v24, v11 row_newbcast:6 row_mask:0xf bank_mask:0xf bound_ctrl:1
	v_fmac_f32_dpp v35, v24, v10 row_newbcast:7 row_mask:0xf bank_mask:0xf bound_ctrl:1
	v_fmac_f32_e32 v39, s66, v36
	v_fmac_f32_dpp v34, v24, v9 row_newbcast:8 row_mask:0xf bank_mask:0xf bound_ctrl:1
	v_fmac_f32_dpp v35, v24, v8 row_newbcast:9 row_mask:0xf bank_mask:0xf bound_ctrl:1
	v_fmac_f32_dpp v34, v24, v7 row_newbcast:10 row_mask:0xf bank_mask:0xf bound_ctrl:1
	v_fmac_f32_dpp v35, v24, v6 row_newbcast:11 row_mask:0xf bank_mask:0xf bound_ctrl:1
	s_nop 0
	v_fmac_f32_dpp v34, v24, v5 row_newbcast:12 row_mask:0xf bank_mask:0xf bound_ctrl:1
	v_fmac_f32_dpp v35, v24, v4 row_newbcast:13 row_mask:0xf bank_mask:0xf bound_ctrl:1
	v_fmac_f32_dpp v34, v24, v3 row_newbcast:14 row_mask:0xf bank_mask:0xf bound_ctrl:1
	v_fmac_f32_dpp v35, v24, v2 row_newbcast:15 row_mask:0xf bank_mask:0xf bound_ctrl:1
	v_fmac_f32_dpp v17, v25, v39 row_newbcast:0 row_mask:0xf bank_mask:0xf bound_ctrl:1
	v_fmac_f32_dpp v16, v25, v39 row_newbcast:1 row_mask:0xf bank_mask:0xf bound_ctrl:1
	v_fmac_f32_dpp v15, v25, v39 row_newbcast:2 row_mask:0xf bank_mask:0xf bound_ctrl:1
	v_fmac_f32_dpp v14, v25, v39 row_newbcast:3 row_mask:0xf bank_mask:0xf bound_ctrl:1
	v_fmac_f32_dpp v13, v25, v39 row_newbcast:4 row_mask:0xf bank_mask:0xf bound_ctrl:1
	v_fmac_f32_dpp v12, v25, v39 row_newbcast:5 row_mask:0xf bank_mask:0xf bound_ctrl:1
	v_fmac_f32_dpp v11, v25, v39 row_newbcast:6 row_mask:0xf bank_mask:0xf bound_ctrl:1
	v_fmac_f32_dpp v10, v25, v39 row_newbcast:7 row_mask:0xf bank_mask:0xf bound_ctrl:1
	v_fmac_f32_dpp v9, v25, v39 row_newbcast:8 row_mask:0xf bank_mask:0xf bound_ctrl:1
	v_fmac_f32_dpp v8, v25, v39 row_newbcast:9 row_mask:0xf bank_mask:0xf bound_ctrl:1
	v_fmac_f32_dpp v7, v25, v39 row_newbcast:10 row_mask:0xf bank_mask:0xf bound_ctrl:1
	v_fmac_f32_dpp v6, v25, v39 row_newbcast:11 row_mask:0xf bank_mask:0xf bound_ctrl:1
	v_fmac_f32_dpp v5, v25, v39 row_newbcast:12 row_mask:0xf bank_mask:0xf bound_ctrl:1
	v_fmac_f32_dpp v4, v25, v39 row_newbcast:13 row_mask:0xf bank_mask:0xf bound_ctrl:1
	v_fmac_f32_dpp v3, v25, v39 row_newbcast:14 row_mask:0xf bank_mask:0xf bound_ctrl:1
	v_fmac_f32_dpp v2, v25, v39 row_newbcast:15 row_mask:0xf bank_mask:0xf bound_ctrl:1
	s_nop 0
	v_add_f32 v34, v34, v35
	s_nop 0
	s_nop 0
	v_mfma_f32_16x16x4_f32 v[224:227], v228, v34, 0
	ds_write_b64 v20, v[22:23] offset:18432
	v_fmac_f32_dpp v17, v26, v38 row_newbcast:0 row_mask:0xf bank_mask:0xf bound_ctrl:1
	v_fmac_f32_dpp v16, v26, v38 row_newbcast:1 row_mask:0xf bank_mask:0xf bound_ctrl:1
	v_fmac_f32_dpp v15, v26, v38 row_newbcast:2 row_mask:0xf bank_mask:0xf bound_ctrl:1
	v_fmac_f32_dpp v14, v26, v38 row_newbcast:3 row_mask:0xf bank_mask:0xf bound_ctrl:1
	v_fmac_f32_dpp v13, v26, v38 row_newbcast:4 row_mask:0xf bank_mask:0xf bound_ctrl:1
	v_fmac_f32_dpp v12, v26, v38 row_newbcast:5 row_mask:0xf bank_mask:0xf bound_ctrl:1
	v_fmac_f32_dpp v11, v26, v38 row_newbcast:6 row_mask:0xf bank_mask:0xf bound_ctrl:1
	v_fmac_f32_dpp v10, v26, v38 row_newbcast:7 row_mask:0xf bank_mask:0xf bound_ctrl:1
	v_fmac_f32_dpp v9, v26, v38 row_newbcast:8 row_mask:0xf bank_mask:0xf bound_ctrl:1
	v_fmac_f32_dpp v8, v26, v38 row_newbcast:9 row_mask:0xf bank_mask:0xf bound_ctrl:1
	v_fmac_f32_dpp v7, v26, v38 row_newbcast:10 row_mask:0xf bank_mask:0xf bound_ctrl:1
	v_fmac_f32_dpp v6, v26, v38 row_newbcast:11 row_mask:0xf bank_mask:0xf bound_ctrl:1
	v_fmac_f32_dpp v5, v26, v38 row_newbcast:12 row_mask:0xf bank_mask:0xf bound_ctrl:1
	v_fmac_f32_dpp v4, v26, v38 row_newbcast:13 row_mask:0xf bank_mask:0xf bound_ctrl:1
	v_fmac_f32_dpp v3, v26, v38 row_newbcast:14 row_mask:0xf bank_mask:0xf bound_ctrl:1
	v_fmac_f32_dpp v2, v26, v38 row_newbcast:15 row_mask:0xf bank_mask:0xf bound_ctrl:1
	v_mul_f32_dpp v22, v27, v17 row_newbcast:0 row_mask:0xf bank_mask:0xf bound_ctrl:1
	v_mul_f32_dpp v23, v27, v16 row_newbcast:1 row_mask:0xf bank_mask:0xf bound_ctrl:1
	v_fmac_f32_dpp v22, v27, v15 row_newbcast:2 row_mask:0xf bank_mask:0xf bound_ctrl:1
	v_fmac_f32_dpp v23, v27, v14 row_newbcast:3 row_mask:0xf bank_mask:0xf bound_ctrl:1
	v_fmac_f32_dpp v22, v27, v13 row_newbcast:4 row_mask:0xf bank_mask:0xf bound_ctrl:1
	v_fmac_f32_dpp v23, v27, v12 row_newbcast:5 row_mask:0xf bank_mask:0xf bound_ctrl:1
	v_fmac_f32_dpp v22, v27, v11 row_newbcast:6 row_mask:0xf bank_mask:0xf bound_ctrl:1
	v_fmac_f32_dpp v23, v27, v10 row_newbcast:7 row_mask:0xf bank_mask:0xf bound_ctrl:1
	s_nop 0
	v_fmac_f32_dpp v22, v27, v9 row_newbcast:8 row_mask:0xf bank_mask:0xf bound_ctrl:1
	v_fmac_f32_dpp v23, v27, v8 row_newbcast:9 row_mask:0xf bank_mask:0xf bound_ctrl:1
	v_fmac_f32_dpp v22, v27, v7 row_newbcast:10 row_mask:0xf bank_mask:0xf bound_ctrl:1
	v_fmac_f32_dpp v23, v27, v6 row_newbcast:11 row_mask:0xf bank_mask:0xf bound_ctrl:1
	s_nop 0
	v_fmac_f32_dpp v22, v27, v5 row_newbcast:12 row_mask:0xf bank_mask:0xf bound_ctrl:1
	v_fmac_f32_dpp v23, v27, v4 row_newbcast:13 row_mask:0xf bank_mask:0xf bound_ctrl:1
	v_fmac_f32_dpp v22, v27, v3 row_newbcast:14 row_mask:0xf bank_mask:0xf bound_ctrl:1
	v_fmac_f32_dpp v23, v27, v2 row_newbcast:15 row_mask:0xf bank_mask:0xf bound_ctrl:1
	s_waitcnt lgkmcnt(0)
	ds_read_b32 v35, v19 offset:23552
	ds_read2st64_b32 v[24:25], v21 offset0:28 offset1:44
	ds_read2st64_b32 v[26:27], v21 offset0:60 offset1:76
	v_mul_f32_dpp v36, v28, v17 row_newbcast:0 row_mask:0xf bank_mask:0xf bound_ctrl:1
	v_mul_f32_dpp v37, v28, v16 row_newbcast:1 row_mask:0xf bank_mask:0xf bound_ctrl:1
	v_fmac_f32_dpp v36, v28, v15 row_newbcast:2 row_mask:0xf bank_mask:0xf bound_ctrl:1
	v_fmac_f32_dpp v37, v28, v14 row_newbcast:3 row_mask:0xf bank_mask:0xf bound_ctrl:1
	v_fma_f32 v34, s65, v39, v224
	v_fmac_f32_dpp v36, v28, v13 row_newbcast:4 row_mask:0xf bank_mask:0xf bound_ctrl:1
	v_fmac_f32_dpp v37, v28, v12 row_newbcast:5 row_mask:0xf bank_mask:0xf bound_ctrl:1
	v_fmac_f32_dpp v36, v28, v11 row_newbcast:6 row_mask:0xf bank_mask:0xf bound_ctrl:1
	v_fmac_f32_dpp v37, v28, v10 row_newbcast:7 row_mask:0xf bank_mask:0xf bound_ctrl:1
	v_fmac_f32_e32 v34, s64, v38
	v_fmac_f32_dpp v36, v28, v9 row_newbcast:8 row_mask:0xf bank_mask:0xf bound_ctrl:1
	v_fmac_f32_dpp v37, v28, v8 row_newbcast:9 row_mask:0xf bank_mask:0xf bound_ctrl:1
	v_fmac_f32_dpp v36, v28, v7 row_newbcast:10 row_mask:0xf bank_mask:0xf bound_ctrl:1
	v_fmac_f32_dpp v37, v28, v6 row_newbcast:11 row_mask:0xf bank_mask:0xf bound_ctrl:1
	s_nop 0
	v_fmac_f32_dpp v36, v28, v5 row_newbcast:12 row_mask:0xf bank_mask:0xf bound_ctrl:1
	v_fmac_f32_dpp v37, v28, v4 row_newbcast:13 row_mask:0xf bank_mask:0xf bound_ctrl:1
	v_fmac_f32_dpp v36, v28, v3 row_newbcast:14 row_mask:0xf bank_mask:0xf bound_ctrl:1
	v_fmac_f32_dpp v37, v28, v2 row_newbcast:15 row_mask:0xf bank_mask:0xf bound_ctrl:1
	v_fmac_f32_dpp v17, v29, v34 row_newbcast:0 row_mask:0xf bank_mask:0xf bound_ctrl:1
	v_fmac_f32_dpp v16, v29, v34 row_newbcast:1 row_mask:0xf bank_mask:0xf bound_ctrl:1
	v_fmac_f32_dpp v15, v29, v34 row_newbcast:2 row_mask:0xf bank_mask:0xf bound_ctrl:1
	v_fmac_f32_dpp v14, v29, v34 row_newbcast:3 row_mask:0xf bank_mask:0xf bound_ctrl:1
	v_fmac_f32_dpp v13, v29, v34 row_newbcast:4 row_mask:0xf bank_mask:0xf bound_ctrl:1
	v_fmac_f32_dpp v12, v29, v34 row_newbcast:5 row_mask:0xf bank_mask:0xf bound_ctrl:1
	v_fmac_f32_dpp v11, v29, v34 row_newbcast:6 row_mask:0xf bank_mask:0xf bound_ctrl:1
	v_fmac_f32_dpp v10, v29, v34 row_newbcast:7 row_mask:0xf bank_mask:0xf bound_ctrl:1
	v_fmac_f32_dpp v9, v29, v34 row_newbcast:8 row_mask:0xf bank_mask:0xf bound_ctrl:1
	v_fmac_f32_dpp v8, v29, v34 row_newbcast:9 row_mask:0xf bank_mask:0xf bound_ctrl:1
	v_fmac_f32_dpp v7, v29, v34 row_newbcast:10 row_mask:0xf bank_mask:0xf bound_ctrl:1
	v_fmac_f32_dpp v6, v29, v34 row_newbcast:11 row_mask:0xf bank_mask:0xf bound_ctrl:1
	v_fmac_f32_dpp v5, v29, v34 row_newbcast:12 row_mask:0xf bank_mask:0xf bound_ctrl:1
	v_fmac_f32_dpp v4, v29, v34 row_newbcast:13 row_mask:0xf bank_mask:0xf bound_ctrl:1
	v_fmac_f32_dpp v3, v29, v34 row_newbcast:14 row_mask:0xf bank_mask:0xf bound_ctrl:1
	v_fmac_f32_dpp v2, v29, v34 row_newbcast:15 row_mask:0xf bank_mask:0xf bound_ctrl:1
	s_nop 0
	v_add_f32 v36, v36, v37
	s_nop 0
	s_nop 0
	v_mfma_f32_16x16x4_f32 v[224:227], v228, v36, 0
	ds_write_b64 v20, v[22:23] offset:20480
	v_fmac_f32_dpp v17, v30, v33 row_newbcast:0 row_mask:0xf bank_mask:0xf bound_ctrl:1
	v_fmac_f32_dpp v16, v30, v33 row_newbcast:1 row_mask:0xf bank_mask:0xf bound_ctrl:1
	v_fmac_f32_dpp v15, v30, v33 row_newbcast:2 row_mask:0xf bank_mask:0xf bound_ctrl:1
	v_fmac_f32_dpp v14, v30, v33 row_newbcast:3 row_mask:0xf bank_mask:0xf bound_ctrl:1
	v_fmac_f32_dpp v13, v30, v33 row_newbcast:4 row_mask:0xf bank_mask:0xf bound_ctrl:1
	v_fmac_f32_dpp v12, v30, v33 row_newbcast:5 row_mask:0xf bank_mask:0xf bound_ctrl:1
	v_fmac_f32_dpp v11, v30, v33 row_newbcast:6 row_mask:0xf bank_mask:0xf bound_ctrl:1
	v_fmac_f32_dpp v10, v30, v33 row_newbcast:7 row_mask:0xf bank_mask:0xf bound_ctrl:1
	v_fmac_f32_dpp v9, v30, v33 row_newbcast:8 row_mask:0xf bank_mask:0xf bound_ctrl:1
	v_fmac_f32_dpp v8, v30, v33 row_newbcast:9 row_mask:0xf bank_mask:0xf bound_ctrl:1
	v_fmac_f32_dpp v7, v30, v33 row_newbcast:10 row_mask:0xf bank_mask:0xf bound_ctrl:1
	v_fmac_f32_dpp v6, v30, v33 row_newbcast:11 row_mask:0xf bank_mask:0xf bound_ctrl:1
	v_fmac_f32_dpp v5, v30, v33 row_newbcast:12 row_mask:0xf bank_mask:0xf bound_ctrl:1
	v_fmac_f32_dpp v4, v30, v33 row_newbcast:13 row_mask:0xf bank_mask:0xf bound_ctrl:1
	v_fmac_f32_dpp v3, v30, v33 row_newbcast:14 row_mask:0xf bank_mask:0xf bound_ctrl:1
	v_fmac_f32_dpp v2, v30, v33 row_newbcast:15 row_mask:0xf bank_mask:0xf bound_ctrl:1
	v_mul_f32_dpp v22, v31, v17 row_newbcast:0 row_mask:0xf bank_mask:0xf bound_ctrl:1
	v_mul_f32_dpp v23, v31, v16 row_newbcast:1 row_mask:0xf bank_mask:0xf bound_ctrl:1
	v_fmac_f32_dpp v22, v31, v15 row_newbcast:2 row_mask:0xf bank_mask:0xf bound_ctrl:1
	v_fmac_f32_dpp v23, v31, v14 row_newbcast:3 row_mask:0xf bank_mask:0xf bound_ctrl:1
	v_fmac_f32_dpp v22, v31, v13 row_newbcast:4 row_mask:0xf bank_mask:0xf bound_ctrl:1
	v_fmac_f32_dpp v23, v31, v12 row_newbcast:5 row_mask:0xf bank_mask:0xf bound_ctrl:1
	v_fmac_f32_dpp v22, v31, v11 row_newbcast:6 row_mask:0xf bank_mask:0xf bound_ctrl:1
	v_fmac_f32_dpp v23, v31, v10 row_newbcast:7 row_mask:0xf bank_mask:0xf bound_ctrl:1
	s_nop 0
	v_fmac_f32_dpp v22, v31, v9 row_newbcast:8 row_mask:0xf bank_mask:0xf bound_ctrl:1
	v_fmac_f32_dpp v23, v31, v8 row_newbcast:9 row_mask:0xf bank_mask:0xf bound_ctrl:1
	v_fmac_f32_dpp v22, v31, v7 row_newbcast:10 row_mask:0xf bank_mask:0xf bound_ctrl:1
	v_fmac_f32_dpp v23, v31, v6 row_newbcast:11 row_mask:0xf bank_mask:0xf bound_ctrl:1
	s_nop 0
	v_fmac_f32_dpp v22, v31, v5 row_newbcast:12 row_mask:0xf bank_mask:0xf bound_ctrl:1
	v_fmac_f32_dpp v23, v31, v4 row_newbcast:13 row_mask:0xf bank_mask:0xf bound_ctrl:1
	v_fmac_f32_dpp v22, v31, v3 row_newbcast:14 row_mask:0xf bank_mask:0xf bound_ctrl:1
	v_fmac_f32_dpp v23, v31, v2 row_newbcast:15 row_mask:0xf bank_mask:0xf bound_ctrl:1
	s_waitcnt lgkmcnt(0)
	ds_read_b32 v37, v19 offset:23808
	ds_read2st64_b32 v[28:29], v21 offset0:29 offset1:45
	ds_read2st64_b32 v[30:31], v21 offset0:61 offset1:77
	v_mul_f32_dpp v38, v24, v17 row_newbcast:0 row_mask:0xf bank_mask:0xf bound_ctrl:1
	v_mul_f32_dpp v39, v24, v16 row_newbcast:1 row_mask:0xf bank_mask:0xf bound_ctrl:1
	v_fmac_f32_dpp v38, v24, v15 row_newbcast:2 row_mask:0xf bank_mask:0xf bound_ctrl:1
	v_fmac_f32_dpp v39, v24, v14 row_newbcast:3 row_mask:0xf bank_mask:0xf bound_ctrl:1
	v_fma_f32 v36, s63, v34, v224
	v_fmac_f32_dpp v38, v24, v13 row_newbcast:4 row_mask:0xf bank_mask:0xf bound_ctrl:1
	v_fmac_f32_dpp v39, v24, v12 row_newbcast:5 row_mask:0xf bank_mask:0xf bound_ctrl:1
	v_fmac_f32_dpp v38, v24, v11 row_newbcast:6 row_mask:0xf bank_mask:0xf bound_ctrl:1
	v_fmac_f32_dpp v39, v24, v10 row_newbcast:7 row_mask:0xf bank_mask:0xf bound_ctrl:1
	v_fmac_f32_e32 v36, s62, v33
	v_fmac_f32_dpp v38, v24, v9 row_newbcast:8 row_mask:0xf bank_mask:0xf bound_ctrl:1
	v_fmac_f32_dpp v39, v24, v8 row_newbcast:9 row_mask:0xf bank_mask:0xf bound_ctrl:1
	v_fmac_f32_dpp v38, v24, v7 row_newbcast:10 row_mask:0xf bank_mask:0xf bound_ctrl:1
	v_fmac_f32_dpp v39, v24, v6 row_newbcast:11 row_mask:0xf bank_mask:0xf bound_ctrl:1
	s_nop 0
	v_fmac_f32_dpp v38, v24, v5 row_newbcast:12 row_mask:0xf bank_mask:0xf bound_ctrl:1
	v_fmac_f32_dpp v39, v24, v4 row_newbcast:13 row_mask:0xf bank_mask:0xf bound_ctrl:1
	v_fmac_f32_dpp v38, v24, v3 row_newbcast:14 row_mask:0xf bank_mask:0xf bound_ctrl:1
	v_fmac_f32_dpp v39, v24, v2 row_newbcast:15 row_mask:0xf bank_mask:0xf bound_ctrl:1
	v_fmac_f32_dpp v17, v25, v36 row_newbcast:0 row_mask:0xf bank_mask:0xf bound_ctrl:1
	v_fmac_f32_dpp v16, v25, v36 row_newbcast:1 row_mask:0xf bank_mask:0xf bound_ctrl:1
	v_fmac_f32_dpp v15, v25, v36 row_newbcast:2 row_mask:0xf bank_mask:0xf bound_ctrl:1
	v_fmac_f32_dpp v14, v25, v36 row_newbcast:3 row_mask:0xf bank_mask:0xf bound_ctrl:1
	v_fmac_f32_dpp v13, v25, v36 row_newbcast:4 row_mask:0xf bank_mask:0xf bound_ctrl:1
	v_fmac_f32_dpp v12, v25, v36 row_newbcast:5 row_mask:0xf bank_mask:0xf bound_ctrl:1
	v_fmac_f32_dpp v11, v25, v36 row_newbcast:6 row_mask:0xf bank_mask:0xf bound_ctrl:1
	v_fmac_f32_dpp v10, v25, v36 row_newbcast:7 row_mask:0xf bank_mask:0xf bound_ctrl:1
	v_fmac_f32_dpp v9, v25, v36 row_newbcast:8 row_mask:0xf bank_mask:0xf bound_ctrl:1
	v_fmac_f32_dpp v8, v25, v36 row_newbcast:9 row_mask:0xf bank_mask:0xf bound_ctrl:1
	v_fmac_f32_dpp v7, v25, v36 row_newbcast:10 row_mask:0xf bank_mask:0xf bound_ctrl:1
	v_fmac_f32_dpp v6, v25, v36 row_newbcast:11 row_mask:0xf bank_mask:0xf bound_ctrl:1
	v_fmac_f32_dpp v5, v25, v36 row_newbcast:12 row_mask:0xf bank_mask:0xf bound_ctrl:1
	v_fmac_f32_dpp v4, v25, v36 row_newbcast:13 row_mask:0xf bank_mask:0xf bound_ctrl:1
	v_fmac_f32_dpp v3, v25, v36 row_newbcast:14 row_mask:0xf bank_mask:0xf bound_ctrl:1
	v_fmac_f32_dpp v2, v25, v36 row_newbcast:15 row_mask:0xf bank_mask:0xf bound_ctrl:1
	s_nop 0
	v_add_f32 v38, v38, v39
	s_nop 0
	s_nop 0
	v_mfma_f32_16x16x4_f32 v[224:227], v228, v38, 0
	ds_write_b64 v20, v[22:23] offset:22528
	v_fmac_f32_dpp v17, v26, v35 row_newbcast:0 row_mask:0xf bank_mask:0xf bound_ctrl:1
	v_fmac_f32_dpp v16, v26, v35 row_newbcast:1 row_mask:0xf bank_mask:0xf bound_ctrl:1
	v_fmac_f32_dpp v15, v26, v35 row_newbcast:2 row_mask:0xf bank_mask:0xf bound_ctrl:1
	v_fmac_f32_dpp v14, v26, v35 row_newbcast:3 row_mask:0xf bank_mask:0xf bound_ctrl:1
	v_fmac_f32_dpp v13, v26, v35 row_newbcast:4 row_mask:0xf bank_mask:0xf bound_ctrl:1
	v_fmac_f32_dpp v12, v26, v35 row_newbcast:5 row_mask:0xf bank_mask:0xf bound_ctrl:1
	v_fmac_f32_dpp v11, v26, v35 row_newbcast:6 row_mask:0xf bank_mask:0xf bound_ctrl:1
	v_fmac_f32_dpp v10, v26, v35 row_newbcast:7 row_mask:0xf bank_mask:0xf bound_ctrl:1
	v_fmac_f32_dpp v9, v26, v35 row_newbcast:8 row_mask:0xf bank_mask:0xf bound_ctrl:1
	v_fmac_f32_dpp v8, v26, v35 row_newbcast:9 row_mask:0xf bank_mask:0xf bound_ctrl:1
	v_fmac_f32_dpp v7, v26, v35 row_newbcast:10 row_mask:0xf bank_mask:0xf bound_ctrl:1
	v_fmac_f32_dpp v6, v26, v35 row_newbcast:11 row_mask:0xf bank_mask:0xf bound_ctrl:1
	v_fmac_f32_dpp v5, v26, v35 row_newbcast:12 row_mask:0xf bank_mask:0xf bound_ctrl:1
	v_fmac_f32_dpp v4, v26, v35 row_newbcast:13 row_mask:0xf bank_mask:0xf bound_ctrl:1
	v_fmac_f32_dpp v3, v26, v35 row_newbcast:14 row_mask:0xf bank_mask:0xf bound_ctrl:1
	v_fmac_f32_dpp v2, v26, v35 row_newbcast:15 row_mask:0xf bank_mask:0xf bound_ctrl:1
	v_mul_f32_dpp v22, v27, v17 row_newbcast:0 row_mask:0xf bank_mask:0xf bound_ctrl:1
	v_mul_f32_dpp v23, v27, v16 row_newbcast:1 row_mask:0xf bank_mask:0xf bound_ctrl:1
	v_fmac_f32_dpp v22, v27, v15 row_newbcast:2 row_mask:0xf bank_mask:0xf bound_ctrl:1
	v_fmac_f32_dpp v23, v27, v14 row_newbcast:3 row_mask:0xf bank_mask:0xf bound_ctrl:1
	v_fmac_f32_dpp v22, v27, v13 row_newbcast:4 row_mask:0xf bank_mask:0xf bound_ctrl:1
	v_fmac_f32_dpp v23, v27, v12 row_newbcast:5 row_mask:0xf bank_mask:0xf bound_ctrl:1
	v_fmac_f32_dpp v22, v27, v11 row_newbcast:6 row_mask:0xf bank_mask:0xf bound_ctrl:1
	v_fmac_f32_dpp v23, v27, v10 row_newbcast:7 row_mask:0xf bank_mask:0xf bound_ctrl:1
	s_nop 0
	v_fmac_f32_dpp v22, v27, v9 row_newbcast:8 row_mask:0xf bank_mask:0xf bound_ctrl:1
	v_fmac_f32_dpp v23, v27, v8 row_newbcast:9 row_mask:0xf bank_mask:0xf bound_ctrl:1
	v_fmac_f32_dpp v22, v27, v7 row_newbcast:10 row_mask:0xf bank_mask:0xf bound_ctrl:1
	v_fmac_f32_dpp v23, v27, v6 row_newbcast:11 row_mask:0xf bank_mask:0xf bound_ctrl:1
	s_nop 0
	v_fmac_f32_dpp v22, v27, v5 row_newbcast:12 row_mask:0xf bank_mask:0xf bound_ctrl:1
	v_fmac_f32_dpp v23, v27, v4 row_newbcast:13 row_mask:0xf bank_mask:0xf bound_ctrl:1
	v_fmac_f32_dpp v22, v27, v3 row_newbcast:14 row_mask:0xf bank_mask:0xf bound_ctrl:1
	v_fmac_f32_dpp v23, v27, v2 row_newbcast:15 row_mask:0xf bank_mask:0xf bound_ctrl:1
	s_waitcnt lgkmcnt(0)
	ds_read_b32 v34, v19 offset:24064
	ds_read2st64_b32 v[24:25], v21 offset0:30 offset1:46
	ds_read2st64_b32 v[26:27], v21 offset0:62 offset1:78
	v_mul_f32_dpp v39, v28, v17 row_newbcast:0 row_mask:0xf bank_mask:0xf bound_ctrl:1
	v_mul_f32_dpp v33, v28, v16 row_newbcast:1 row_mask:0xf bank_mask:0xf bound_ctrl:1
	v_fmac_f32_dpp v39, v28, v15 row_newbcast:2 row_mask:0xf bank_mask:0xf bound_ctrl:1
	v_fmac_f32_dpp v33, v28, v14 row_newbcast:3 row_mask:0xf bank_mask:0xf bound_ctrl:1
	v_fma_f32 v38, s59, v36, v224
	v_fmac_f32_dpp v39, v28, v13 row_newbcast:4 row_mask:0xf bank_mask:0xf bound_ctrl:1
	v_fmac_f32_dpp v33, v28, v12 row_newbcast:5 row_mask:0xf bank_mask:0xf bound_ctrl:1
	v_fmac_f32_dpp v39, v28, v11 row_newbcast:6 row_mask:0xf bank_mask:0xf bound_ctrl:1
	v_fmac_f32_dpp v33, v28, v10 row_newbcast:7 row_mask:0xf bank_mask:0xf bound_ctrl:1
	v_fmac_f32_e32 v38, s58, v35
	v_fmac_f32_dpp v39, v28, v9 row_newbcast:8 row_mask:0xf bank_mask:0xf bound_ctrl:1
	v_fmac_f32_dpp v33, v28, v8 row_newbcast:9 row_mask:0xf bank_mask:0xf bound_ctrl:1
	v_fmac_f32_dpp v39, v28, v7 row_newbcast:10 row_mask:0xf bank_mask:0xf bound_ctrl:1
	v_fmac_f32_dpp v33, v28, v6 row_newbcast:11 row_mask:0xf bank_mask:0xf bound_ctrl:1
	s_nop 0
	v_fmac_f32_dpp v39, v28, v5 row_newbcast:12 row_mask:0xf bank_mask:0xf bound_ctrl:1
	v_fmac_f32_dpp v33, v28, v4 row_newbcast:13 row_mask:0xf bank_mask:0xf bound_ctrl:1
	v_fmac_f32_dpp v39, v28, v3 row_newbcast:14 row_mask:0xf bank_mask:0xf bound_ctrl:1
	v_fmac_f32_dpp v33, v28, v2 row_newbcast:15 row_mask:0xf bank_mask:0xf bound_ctrl:1
	v_fmac_f32_dpp v17, v29, v38 row_newbcast:0 row_mask:0xf bank_mask:0xf bound_ctrl:1
	v_fmac_f32_dpp v16, v29, v38 row_newbcast:1 row_mask:0xf bank_mask:0xf bound_ctrl:1
	v_fmac_f32_dpp v15, v29, v38 row_newbcast:2 row_mask:0xf bank_mask:0xf bound_ctrl:1
	v_fmac_f32_dpp v14, v29, v38 row_newbcast:3 row_mask:0xf bank_mask:0xf bound_ctrl:1
	v_fmac_f32_dpp v13, v29, v38 row_newbcast:4 row_mask:0xf bank_mask:0xf bound_ctrl:1
	v_fmac_f32_dpp v12, v29, v38 row_newbcast:5 row_mask:0xf bank_mask:0xf bound_ctrl:1
	v_fmac_f32_dpp v11, v29, v38 row_newbcast:6 row_mask:0xf bank_mask:0xf bound_ctrl:1
	v_fmac_f32_dpp v10, v29, v38 row_newbcast:7 row_mask:0xf bank_mask:0xf bound_ctrl:1
	v_fmac_f32_dpp v9, v29, v38 row_newbcast:8 row_mask:0xf bank_mask:0xf bound_ctrl:1
	v_fmac_f32_dpp v8, v29, v38 row_newbcast:9 row_mask:0xf bank_mask:0xf bound_ctrl:1
	v_fmac_f32_dpp v7, v29, v38 row_newbcast:10 row_mask:0xf bank_mask:0xf bound_ctrl:1
	v_fmac_f32_dpp v6, v29, v38 row_newbcast:11 row_mask:0xf bank_mask:0xf bound_ctrl:1
	v_fmac_f32_dpp v5, v29, v38 row_newbcast:12 row_mask:0xf bank_mask:0xf bound_ctrl:1
	v_fmac_f32_dpp v4, v29, v38 row_newbcast:13 row_mask:0xf bank_mask:0xf bound_ctrl:1
	v_fmac_f32_dpp v3, v29, v38 row_newbcast:14 row_mask:0xf bank_mask:0xf bound_ctrl:1
	v_fmac_f32_dpp v2, v29, v38 row_newbcast:15 row_mask:0xf bank_mask:0xf bound_ctrl:1
	s_nop 0
	v_add_f32 v39, v39, v33
	s_nop 0
	s_nop 0
	v_mfma_f32_16x16x4_f32 v[224:227], v228, v39, 0
	ds_write_b64 v20, v[22:23] offset:24576
	v_fmac_f32_dpp v17, v30, v37 row_newbcast:0 row_mask:0xf bank_mask:0xf bound_ctrl:1
	v_fmac_f32_dpp v16, v30, v37 row_newbcast:1 row_mask:0xf bank_mask:0xf bound_ctrl:1
	v_fmac_f32_dpp v15, v30, v37 row_newbcast:2 row_mask:0xf bank_mask:0xf bound_ctrl:1
	v_fmac_f32_dpp v14, v30, v37 row_newbcast:3 row_mask:0xf bank_mask:0xf bound_ctrl:1
	v_fmac_f32_dpp v13, v30, v37 row_newbcast:4 row_mask:0xf bank_mask:0xf bound_ctrl:1
	v_fmac_f32_dpp v12, v30, v37 row_newbcast:5 row_mask:0xf bank_mask:0xf bound_ctrl:1
	v_fmac_f32_dpp v11, v30, v37 row_newbcast:6 row_mask:0xf bank_mask:0xf bound_ctrl:1
	v_fmac_f32_dpp v10, v30, v37 row_newbcast:7 row_mask:0xf bank_mask:0xf bound_ctrl:1
	v_fmac_f32_dpp v9, v30, v37 row_newbcast:8 row_mask:0xf bank_mask:0xf bound_ctrl:1
	v_fmac_f32_dpp v8, v30, v37 row_newbcast:9 row_mask:0xf bank_mask:0xf bound_ctrl:1
	v_fmac_f32_dpp v7, v30, v37 row_newbcast:10 row_mask:0xf bank_mask:0xf bound_ctrl:1
	v_fmac_f32_dpp v6, v30, v37 row_newbcast:11 row_mask:0xf bank_mask:0xf bound_ctrl:1
	v_fmac_f32_dpp v5, v30, v37 row_newbcast:12 row_mask:0xf bank_mask:0xf bound_ctrl:1
	v_fmac_f32_dpp v4, v30, v37 row_newbcast:13 row_mask:0xf bank_mask:0xf bound_ctrl:1
	v_fmac_f32_dpp v3, v30, v37 row_newbcast:14 row_mask:0xf bank_mask:0xf bound_ctrl:1
	v_fmac_f32_dpp v2, v30, v37 row_newbcast:15 row_mask:0xf bank_mask:0xf bound_ctrl:1
	v_mul_f32_dpp v28, v31, v17 row_newbcast:0 row_mask:0xf bank_mask:0xf bound_ctrl:1
	v_mul_f32_dpp v29, v31, v16 row_newbcast:1 row_mask:0xf bank_mask:0xf bound_ctrl:1
	v_fmac_f32_dpp v28, v31, v15 row_newbcast:2 row_mask:0xf bank_mask:0xf bound_ctrl:1
	v_fmac_f32_dpp v29, v31, v14 row_newbcast:3 row_mask:0xf bank_mask:0xf bound_ctrl:1
	v_fmac_f32_dpp v28, v31, v13 row_newbcast:4 row_mask:0xf bank_mask:0xf bound_ctrl:1
	v_fmac_f32_dpp v29, v31, v12 row_newbcast:5 row_mask:0xf bank_mask:0xf bound_ctrl:1
	v_fmac_f32_dpp v28, v31, v11 row_newbcast:6 row_mask:0xf bank_mask:0xf bound_ctrl:1
	v_fmac_f32_dpp v29, v31, v10 row_newbcast:7 row_mask:0xf bank_mask:0xf bound_ctrl:1
	s_nop 0
	v_fmac_f32_dpp v28, v31, v9 row_newbcast:8 row_mask:0xf bank_mask:0xf bound_ctrl:1
	v_fmac_f32_dpp v29, v31, v8 row_newbcast:9 row_mask:0xf bank_mask:0xf bound_ctrl:1
	v_fmac_f32_dpp v28, v31, v7 row_newbcast:10 row_mask:0xf bank_mask:0xf bound_ctrl:1
	v_fmac_f32_dpp v29, v31, v6 row_newbcast:11 row_mask:0xf bank_mask:0xf bound_ctrl:1
	s_nop 0
	v_fmac_f32_dpp v28, v31, v5 row_newbcast:12 row_mask:0xf bank_mask:0xf bound_ctrl:1
	v_fmac_f32_dpp v29, v31, v4 row_newbcast:13 row_mask:0xf bank_mask:0xf bound_ctrl:1
	v_fmac_f32_dpp v28, v31, v3 row_newbcast:14 row_mask:0xf bank_mask:0xf bound_ctrl:1
	v_fmac_f32_dpp v29, v31, v2 row_newbcast:15 row_mask:0xf bank_mask:0xf bound_ctrl:1
	s_waitcnt lgkmcnt(0)
	ds_read_b32 v19, v19 offset:24320
	ds_read2st64_b32 v[30:31], v21 offset0:31 offset1:47
	ds_read2st64_b32 v[32:33], v21 offset0:63 offset1:79
	v_mul_f32_dpp v22, v24, v17 row_newbcast:0 row_mask:0xf bank_mask:0xf bound_ctrl:1
	v_mul_f32_dpp v35, v24, v16 row_newbcast:1 row_mask:0xf bank_mask:0xf bound_ctrl:1
	v_fmac_f32_dpp v22, v24, v15 row_newbcast:2 row_mask:0xf bank_mask:0xf bound_ctrl:1
	v_fmac_f32_dpp v35, v24, v14 row_newbcast:3 row_mask:0xf bank_mask:0xf bound_ctrl:1
	v_fma_f32 v39, s57, v38, v224
	v_fmac_f32_dpp v22, v24, v13 row_newbcast:4 row_mask:0xf bank_mask:0xf bound_ctrl:1
	v_fmac_f32_dpp v35, v24, v12 row_newbcast:5 row_mask:0xf bank_mask:0xf bound_ctrl:1
	v_fmac_f32_dpp v22, v24, v11 row_newbcast:6 row_mask:0xf bank_mask:0xf bound_ctrl:1
	v_fmac_f32_dpp v35, v24, v10 row_newbcast:7 row_mask:0xf bank_mask:0xf bound_ctrl:1
	v_fmac_f32_e32 v39, s56, v37
	v_fmac_f32_dpp v22, v24, v9 row_newbcast:8 row_mask:0xf bank_mask:0xf bound_ctrl:1
	v_fmac_f32_dpp v35, v24, v8 row_newbcast:9 row_mask:0xf bank_mask:0xf bound_ctrl:1
	v_fmac_f32_dpp v22, v24, v7 row_newbcast:10 row_mask:0xf bank_mask:0xf bound_ctrl:1
	v_fmac_f32_dpp v35, v24, v6 row_newbcast:11 row_mask:0xf bank_mask:0xf bound_ctrl:1
	s_nop 0
	v_fmac_f32_dpp v22, v24, v5 row_newbcast:12 row_mask:0xf bank_mask:0xf bound_ctrl:1
	v_fmac_f32_dpp v35, v24, v4 row_newbcast:13 row_mask:0xf bank_mask:0xf bound_ctrl:1
	v_fmac_f32_dpp v22, v24, v3 row_newbcast:14 row_mask:0xf bank_mask:0xf bound_ctrl:1
	v_fmac_f32_dpp v35, v24, v2 row_newbcast:15 row_mask:0xf bank_mask:0xf bound_ctrl:1
	v_fmac_f32_dpp v17, v25, v39 row_newbcast:0 row_mask:0xf bank_mask:0xf bound_ctrl:1
	v_fmac_f32_dpp v16, v25, v39 row_newbcast:1 row_mask:0xf bank_mask:0xf bound_ctrl:1
	v_fmac_f32_dpp v15, v25, v39 row_newbcast:2 row_mask:0xf bank_mask:0xf bound_ctrl:1
	v_fmac_f32_dpp v14, v25, v39 row_newbcast:3 row_mask:0xf bank_mask:0xf bound_ctrl:1
	v_fmac_f32_dpp v13, v25, v39 row_newbcast:4 row_mask:0xf bank_mask:0xf bound_ctrl:1
	v_fmac_f32_dpp v12, v25, v39 row_newbcast:5 row_mask:0xf bank_mask:0xf bound_ctrl:1
	v_fmac_f32_dpp v11, v25, v39 row_newbcast:6 row_mask:0xf bank_mask:0xf bound_ctrl:1
	v_fmac_f32_dpp v10, v25, v39 row_newbcast:7 row_mask:0xf bank_mask:0xf bound_ctrl:1
	v_fmac_f32_dpp v9, v25, v39 row_newbcast:8 row_mask:0xf bank_mask:0xf bound_ctrl:1
	v_fmac_f32_dpp v8, v25, v39 row_newbcast:9 row_mask:0xf bank_mask:0xf bound_ctrl:1
	v_fmac_f32_dpp v7, v25, v39 row_newbcast:10 row_mask:0xf bank_mask:0xf bound_ctrl:1
	v_fmac_f32_dpp v6, v25, v39 row_newbcast:11 row_mask:0xf bank_mask:0xf bound_ctrl:1
	v_fmac_f32_dpp v5, v25, v39 row_newbcast:12 row_mask:0xf bank_mask:0xf bound_ctrl:1
	v_fmac_f32_dpp v4, v25, v39 row_newbcast:13 row_mask:0xf bank_mask:0xf bound_ctrl:1
	v_fmac_f32_dpp v3, v25, v39 row_newbcast:14 row_mask:0xf bank_mask:0xf bound_ctrl:1
	v_fmac_f32_dpp v2, v25, v39 row_newbcast:15 row_mask:0xf bank_mask:0xf bound_ctrl:1
	s_nop 0
	v_add_f32 v22, v22, v35
	s_nop 0
	s_nop 0
	v_mfma_f32_16x16x4_f32 v[224:227], v228, v22, 0
	ds_write_b64 v20, v[28:29] offset:26624
	v_fmac_f32_dpp v17, v26, v34 row_newbcast:0 row_mask:0xf bank_mask:0xf bound_ctrl:1
	v_fmac_f32_dpp v16, v26, v34 row_newbcast:1 row_mask:0xf bank_mask:0xf bound_ctrl:1
	v_fmac_f32_dpp v15, v26, v34 row_newbcast:2 row_mask:0xf bank_mask:0xf bound_ctrl:1
	v_fmac_f32_dpp v14, v26, v34 row_newbcast:3 row_mask:0xf bank_mask:0xf bound_ctrl:1
	v_fmac_f32_dpp v13, v26, v34 row_newbcast:4 row_mask:0xf bank_mask:0xf bound_ctrl:1
	v_fmac_f32_dpp v12, v26, v34 row_newbcast:5 row_mask:0xf bank_mask:0xf bound_ctrl:1
	v_fmac_f32_dpp v11, v26, v34 row_newbcast:6 row_mask:0xf bank_mask:0xf bound_ctrl:1
	v_fmac_f32_dpp v10, v26, v34 row_newbcast:7 row_mask:0xf bank_mask:0xf bound_ctrl:1
	v_fmac_f32_dpp v9, v26, v34 row_newbcast:8 row_mask:0xf bank_mask:0xf bound_ctrl:1
	v_fmac_f32_dpp v8, v26, v34 row_newbcast:9 row_mask:0xf bank_mask:0xf bound_ctrl:1
	v_fmac_f32_dpp v7, v26, v34 row_newbcast:10 row_mask:0xf bank_mask:0xf bound_ctrl:1
	v_fmac_f32_dpp v6, v26, v34 row_newbcast:11 row_mask:0xf bank_mask:0xf bound_ctrl:1
	v_fmac_f32_dpp v5, v26, v34 row_newbcast:12 row_mask:0xf bank_mask:0xf bound_ctrl:1
	v_fmac_f32_dpp v4, v26, v34 row_newbcast:13 row_mask:0xf bank_mask:0xf bound_ctrl:1
	v_fmac_f32_dpp v3, v26, v34 row_newbcast:14 row_mask:0xf bank_mask:0xf bound_ctrl:1
	v_fmac_f32_dpp v2, v26, v34 row_newbcast:15 row_mask:0xf bank_mask:0xf bound_ctrl:1
	v_mul_f32_dpp v24, v27, v17 row_newbcast:0 row_mask:0xf bank_mask:0xf bound_ctrl:1
	v_mul_f32_dpp v25, v27, v16 row_newbcast:1 row_mask:0xf bank_mask:0xf bound_ctrl:1
	v_fmac_f32_dpp v24, v27, v15 row_newbcast:2 row_mask:0xf bank_mask:0xf bound_ctrl:1
	v_fmac_f32_dpp v25, v27, v14 row_newbcast:3 row_mask:0xf bank_mask:0xf bound_ctrl:1
	v_fmac_f32_dpp v24, v27, v13 row_newbcast:4 row_mask:0xf bank_mask:0xf bound_ctrl:1
	v_fmac_f32_dpp v25, v27, v12 row_newbcast:5 row_mask:0xf bank_mask:0xf bound_ctrl:1
	v_fmac_f32_dpp v24, v27, v11 row_newbcast:6 row_mask:0xf bank_mask:0xf bound_ctrl:1
	v_fmac_f32_dpp v25, v27, v10 row_newbcast:7 row_mask:0xf bank_mask:0xf bound_ctrl:1
	s_nop 0
	v_fmac_f32_dpp v24, v27, v9 row_newbcast:8 row_mask:0xf bank_mask:0xf bound_ctrl:1
	v_fmac_f32_dpp v25, v27, v8 row_newbcast:9 row_mask:0xf bank_mask:0xf bound_ctrl:1
	v_fmac_f32_dpp v24, v27, v7 row_newbcast:10 row_mask:0xf bank_mask:0xf bound_ctrl:1
	v_fmac_f32_dpp v25, v27, v6 row_newbcast:11 row_mask:0xf bank_mask:0xf bound_ctrl:1
	s_nop 0
	v_fmac_f32_dpp v24, v27, v5 row_newbcast:12 row_mask:0xf bank_mask:0xf bound_ctrl:1
	v_fmac_f32_dpp v25, v27, v4 row_newbcast:13 row_mask:0xf bank_mask:0xf bound_ctrl:1
	v_fmac_f32_dpp v24, v27, v3 row_newbcast:14 row_mask:0xf bank_mask:0xf bound_ctrl:1
	v_fmac_f32_dpp v25, v27, v2 row_newbcast:15 row_mask:0xf bank_mask:0xf bound_ctrl:1
	s_waitcnt lgkmcnt(0)
	v_mul_f32_dpp v18, v30, v17 row_newbcast:0 row_mask:0xf bank_mask:0xf bound_ctrl:1
	v_mul_f32_dpp v27, v30, v16 row_newbcast:1 row_mask:0xf bank_mask:0xf bound_ctrl:1
	v_fmac_f32_dpp v18, v30, v15 row_newbcast:2 row_mask:0xf bank_mask:0xf bound_ctrl:1
	v_fmac_f32_dpp v27, v30, v14 row_newbcast:3 row_mask:0xf bank_mask:0xf bound_ctrl:1
	s_nop 0
	v_fmac_f32_dpp v18, v30, v13 row_newbcast:4 row_mask:0xf bank_mask:0xf bound_ctrl:1
	v_fmac_f32_dpp v27, v30, v12 row_newbcast:5 row_mask:0xf bank_mask:0xf bound_ctrl:1
	v_fmac_f32_dpp v18, v30, v11 row_newbcast:6 row_mask:0xf bank_mask:0xf bound_ctrl:1
	v_fmac_f32_dpp v27, v30, v10 row_newbcast:7 row_mask:0xf bank_mask:0xf bound_ctrl:1
	v_fma_f32 v22, s53, v39, v224
	v_fmac_f32_dpp v18, v30, v9 row_newbcast:8 row_mask:0xf bank_mask:0xf bound_ctrl:1
	v_fmac_f32_dpp v27, v30, v8 row_newbcast:9 row_mask:0xf bank_mask:0xf bound_ctrl:1
	v_fmac_f32_dpp v18, v30, v7 row_newbcast:10 row_mask:0xf bank_mask:0xf bound_ctrl:1
	v_fmac_f32_dpp v27, v30, v6 row_newbcast:11 row_mask:0xf bank_mask:0xf bound_ctrl:1
	v_fmac_f32_e32 v22, s48, v34
	v_fmac_f32_dpp v18, v30, v5 row_newbcast:12 row_mask:0xf bank_mask:0xf bound_ctrl:1
	v_fmac_f32_dpp v27, v30, v4 row_newbcast:13 row_mask:0xf bank_mask:0xf bound_ctrl:1
	v_fmac_f32_dpp v18, v30, v3 row_newbcast:14 row_mask:0xf bank_mask:0xf bound_ctrl:1
	v_fmac_f32_dpp v27, v30, v2 row_newbcast:15 row_mask:0xf bank_mask:0xf bound_ctrl:1
	v_fmac_f32_dpp v17, v31, v22 row_newbcast:0 row_mask:0xf bank_mask:0xf bound_ctrl:1
	v_fmac_f32_dpp v16, v31, v22 row_newbcast:1 row_mask:0xf bank_mask:0xf bound_ctrl:1
	v_fmac_f32_dpp v15, v31, v22 row_newbcast:2 row_mask:0xf bank_mask:0xf bound_ctrl:1
	v_fmac_f32_dpp v14, v31, v22 row_newbcast:3 row_mask:0xf bank_mask:0xf bound_ctrl:1
	v_fmac_f32_dpp v13, v31, v22 row_newbcast:4 row_mask:0xf bank_mask:0xf bound_ctrl:1
	v_fmac_f32_dpp v12, v31, v22 row_newbcast:5 row_mask:0xf bank_mask:0xf bound_ctrl:1
	v_fmac_f32_dpp v11, v31, v22 row_newbcast:6 row_mask:0xf bank_mask:0xf bound_ctrl:1
	v_fmac_f32_dpp v10, v31, v22 row_newbcast:7 row_mask:0xf bank_mask:0xf bound_ctrl:1
	v_fmac_f32_dpp v9, v31, v22 row_newbcast:8 row_mask:0xf bank_mask:0xf bound_ctrl:1
	v_fmac_f32_dpp v8, v31, v22 row_newbcast:9 row_mask:0xf bank_mask:0xf bound_ctrl:1
	v_fmac_f32_dpp v7, v31, v22 row_newbcast:10 row_mask:0xf bank_mask:0xf bound_ctrl:1
	v_fmac_f32_dpp v6, v31, v22 row_newbcast:11 row_mask:0xf bank_mask:0xf bound_ctrl:1
	v_fmac_f32_dpp v5, v31, v22 row_newbcast:12 row_mask:0xf bank_mask:0xf bound_ctrl:1
	v_fmac_f32_dpp v4, v31, v22 row_newbcast:13 row_mask:0xf bank_mask:0xf bound_ctrl:1
	v_fmac_f32_dpp v3, v31, v22 row_newbcast:14 row_mask:0xf bank_mask:0xf bound_ctrl:1
	v_fmac_f32_dpp v2, v31, v22 row_newbcast:15 row_mask:0xf bank_mask:0xf bound_ctrl:1
	s_nop 0
	v_add_f32 v18, v18, v27
	s_nop 0
	s_nop 0
	v_mfma_f32_16x16x4_f32 v[224:227], v228, v18, 0
	ds_write_b64 v20, v[24:25] offset:28672
	v_fmac_f32_dpp v17, v32, v19 row_newbcast:0 row_mask:0xf bank_mask:0xf bound_ctrl:1
	v_fmac_f32_dpp v16, v32, v19 row_newbcast:1 row_mask:0xf bank_mask:0xf bound_ctrl:1
	v_fmac_f32_dpp v15, v32, v19 row_newbcast:2 row_mask:0xf bank_mask:0xf bound_ctrl:1
	v_fmac_f32_dpp v14, v32, v19 row_newbcast:3 row_mask:0xf bank_mask:0xf bound_ctrl:1
	v_fmac_f32_dpp v13, v32, v19 row_newbcast:4 row_mask:0xf bank_mask:0xf bound_ctrl:1
	v_fmac_f32_dpp v12, v32, v19 row_newbcast:5 row_mask:0xf bank_mask:0xf bound_ctrl:1
	v_fmac_f32_dpp v11, v32, v19 row_newbcast:6 row_mask:0xf bank_mask:0xf bound_ctrl:1
	v_fmac_f32_dpp v10, v32, v19 row_newbcast:7 row_mask:0xf bank_mask:0xf bound_ctrl:1
	v_fmac_f32_dpp v9, v32, v19 row_newbcast:8 row_mask:0xf bank_mask:0xf bound_ctrl:1
	v_fmac_f32_dpp v8, v32, v19 row_newbcast:9 row_mask:0xf bank_mask:0xf bound_ctrl:1
	v_fmac_f32_dpp v7, v32, v19 row_newbcast:10 row_mask:0xf bank_mask:0xf bound_ctrl:1
	v_fmac_f32_dpp v6, v32, v19 row_newbcast:11 row_mask:0xf bank_mask:0xf bound_ctrl:1
	v_fmac_f32_dpp v5, v32, v19 row_newbcast:12 row_mask:0xf bank_mask:0xf bound_ctrl:1
	v_fmac_f32_dpp v4, v32, v19 row_newbcast:13 row_mask:0xf bank_mask:0xf bound_ctrl:1
	v_fmac_f32_dpp v3, v32, v19 row_newbcast:14 row_mask:0xf bank_mask:0xf bound_ctrl:1
	v_fmac_f32_dpp v2, v32, v19 row_newbcast:15 row_mask:0xf bank_mask:0xf bound_ctrl:1
	v_mul_f32_dpp v24, v33, v17 row_newbcast:0 row_mask:0xf bank_mask:0xf bound_ctrl:1
	v_mul_f32_dpp v25, v33, v16 row_newbcast:1 row_mask:0xf bank_mask:0xf bound_ctrl:1
	v_fmac_f32_dpp v24, v33, v15 row_newbcast:2 row_mask:0xf bank_mask:0xf bound_ctrl:1
	v_fmac_f32_dpp v25, v33, v14 row_newbcast:3 row_mask:0xf bank_mask:0xf bound_ctrl:1
	v_fmac_f32_dpp v24, v33, v13 row_newbcast:4 row_mask:0xf bank_mask:0xf bound_ctrl:1
	v_fmac_f32_dpp v25, v33, v12 row_newbcast:5 row_mask:0xf bank_mask:0xf bound_ctrl:1
	v_fmac_f32_dpp v24, v33, v11 row_newbcast:6 row_mask:0xf bank_mask:0xf bound_ctrl:1
	v_fmac_f32_dpp v25, v33, v10 row_newbcast:7 row_mask:0xf bank_mask:0xf bound_ctrl:1
	s_nop 0
	v_fmac_f32_dpp v24, v33, v9 row_newbcast:8 row_mask:0xf bank_mask:0xf bound_ctrl:1
	v_fmac_f32_dpp v25, v33, v8 row_newbcast:9 row_mask:0xf bank_mask:0xf bound_ctrl:1
	v_fmac_f32_dpp v24, v33, v7 row_newbcast:10 row_mask:0xf bank_mask:0xf bound_ctrl:1
	v_fmac_f32_dpp v25, v33, v6 row_newbcast:11 row_mask:0xf bank_mask:0xf bound_ctrl:1
	s_nop 0
	v_fmac_f32_dpp v24, v33, v5 row_newbcast:12 row_mask:0xf bank_mask:0xf bound_ctrl:1
	v_fmac_f32_dpp v25, v33, v4 row_newbcast:13 row_mask:0xf bank_mask:0xf bound_ctrl:1
	v_fmac_f32_dpp v24, v33, v3 row_newbcast:14 row_mask:0xf bank_mask:0xf bound_ctrl:1
	v_fmac_f32_dpp v25, v33, v2 row_newbcast:15 row_mask:0xf bank_mask:0xf bound_ctrl:1
	v_mov_b32_e32 v18, v224
	ds_read_b32 v21, v21 offset:3840
	s_waitcnt lgkmcnt(0)
	v_mul_f32_dpp v17, v21, v17 row_newbcast:0 row_mask:0xf bank_mask:0xf bound_ctrl:1
	v_mul_f32_dpp v16, v21, v16 row_newbcast:1 row_mask:0xf bank_mask:0xf bound_ctrl:1
	v_mul_f32_dpp v15, v21, v15 row_newbcast:2 row_mask:0xf bank_mask:0xf bound_ctrl:1
	v_mul_f32_dpp v14, v21, v14 row_newbcast:3 row_mask:0xf bank_mask:0xf bound_ctrl:1
	v_mul_f32_dpp v13, v21, v13 row_newbcast:4 row_mask:0xf bank_mask:0xf bound_ctrl:1
	v_mul_f32_dpp v12, v21, v12 row_newbcast:5 row_mask:0xf bank_mask:0xf bound_ctrl:1
	v_mul_f32_dpp v11, v21, v11 row_newbcast:6 row_mask:0xf bank_mask:0xf bound_ctrl:1
	v_mul_f32_dpp v10, v21, v10 row_newbcast:7 row_mask:0xf bank_mask:0xf bound_ctrl:1
	v_mul_f32_dpp v9, v21, v9 row_newbcast:8 row_mask:0xf bank_mask:0xf bound_ctrl:1
	v_mul_f32_dpp v8, v21, v8 row_newbcast:9 row_mask:0xf bank_mask:0xf bound_ctrl:1
	v_mul_f32_dpp v7, v21, v7 row_newbcast:10 row_mask:0xf bank_mask:0xf bound_ctrl:1
	v_mul_f32_dpp v6, v21, v6 row_newbcast:11 row_mask:0xf bank_mask:0xf bound_ctrl:1
	v_mul_f32_dpp v5, v21, v5 row_newbcast:12 row_mask:0xf bank_mask:0xf bound_ctrl:1
	v_mul_f32_dpp v4, v21, v4 row_newbcast:13 row_mask:0xf bank_mask:0xf bound_ctrl:1
	v_mul_f32_dpp v3, v21, v3 row_newbcast:14 row_mask:0xf bank_mask:0xf bound_ctrl:1
	v_mul_f32_dpp v2, v21, v2 row_newbcast:15 row_mask:0xf bank_mask:0xf bound_ctrl:1
	ds_write_b64 v20, v[24:25] offset:30720
	s_waitcnt lgkmcnt(0)
	s_barrier
	s_cbranch_scc1 .LBB0_583
